# loop-edge edit: GEMM k-loop back-edge branch taken before the phase-8 barrier (barrier moved to the loop head / fall-through exit)
# baseline (speedup 1.0000x reference)
.LBB0_376:
	v_add_u32_e32 v222, 0x18000, v147
	v_add_u32_e32 v223, 0x1c000, v147
	ds_read_b128 v[152:155], v149
	ds_read_b128 v[156:159], v149 offset:1024
	ds_read_b128 v[160:163], v149 offset:2048
	ds_read_b128 v[168:171], v149 offset:3072
	ds_read_b128 v[172:175], v150
	ds_read_b128 v[176:179], v150 offset:1024
	ds_read_b128 v[180:183], v150 offset:2048
	ds_read_b128 v[184:187], v150 offset:3072
	ds_read_b128 v[188:191], v150 offset:4096
	ds_read_b128 v[192:195], v150 offset:5120
	ds_read_b128 v[196:199], v150 offset:6144
	ds_read_b128 v[200:203], v150 offset:7168
	s_ashr_i32 s17, s16, 31
	v_cmp_lt_i64_e32 vcc, s[20:21], v[140:141]
	s_lshl_b64 s[20:21], s[16:17], 20
	s_add_u32 s20, s35, s20
	s_addc_u32 s21, s36, s21
	s_and_b64 s[22:23], vcc, exec
	s_cselect_b32 s17, s21, s25
	s_cselect_b32 s19, s20, s24
	s_ashr_i32 s15, s14, 31
	s_lshl_b64 s[22:23], s[14:15], 20
	s_add_u32 s22, s37, s22
	s_addc_u32 s23, s38, s23
	s_and_b64 s[28:29], vcc, exec
	s_cselect_b32 s15, s23, s27
	s_cselect_b32 s51, s22, s26
	s_add_u32 s24, s24, 0x80080
	s_addc_u32 s25, s25, 0
	s_add_u32 s52, s26, 0x100
	s_addc_u32 s53, s27, 0
	s_mov_b32 s54, -2
	s_add_u32 s26, s24, 0xfff80080
	s_addc_u32 s27, s25, -1
	s_cmp_eq_u32 s54, 28
	s_cselect_b32 s29, s17, s27
	s_cselect_b32 s28, s19, s26
	s_cselect_b32 s27, s15, s53
	s_cselect_b32 s26, s51, s52
	s_add_i32 m0, s39, 0xc000
	s_nop 0
	global_load_lds_dwordx4 v136, s[24:25]
	s_add_i32 m0, s39, 0xe000
	s_nop 0
	global_load_lds_dwordx4 v138, s[24:25]
	s_waitcnt vmcnt(10)
	s_barrier
	s_waitcnt lgkmcnt(0)
	v_mfma_f32_16x16x32_bf16 v[126:129], v[152:155], v[172:175], 0
	ds_read_b128 v[204:207], v151
	v_mfma_f32_16x16x32_bf16 v[122:125], v[160:163], v[172:175], 0
	v_mfma_f32_16x16x32_bf16 v[118:121], v[152:155], v[180:183], 0
	v_mfma_f32_16x16x32_bf16 v[114:117], v[160:163], v[180:183], 0
	v_mfma_f32_16x16x32_bf16 v[102:105], v[152:155], v[188:191], 0
	ds_read_b128 v[208:211], v151 offset:1024
	v_mfma_f32_16x16x32_bf16 v[98:101], v[160:163], v[188:191], 0
	v_mfma_f32_16x16x32_bf16 v[86:89], v[152:155], v[196:199], 0
	v_mfma_f32_16x16x32_bf16 v[82:85], v[160:163], v[196:199], 0
	v_mfma_f32_16x16x32_bf16 v[126:129], v[156:159], v[176:179], v[126:129]
	ds_read_b128 v[212:215], v151 offset:2048
	v_mfma_f32_16x16x32_bf16 v[122:125], v[168:171], v[176:179], v[122:125]
	v_mfma_f32_16x16x32_bf16 v[118:121], v[156:159], v[184:187], v[118:121]
	v_mfma_f32_16x16x32_bf16 v[114:117], v[168:171], v[184:187], v[114:117]
	v_mfma_f32_16x16x32_bf16 v[102:105], v[156:159], v[192:195], v[102:105]
	ds_read_b128 v[216:219], v151 offset:3072
	v_mfma_f32_16x16x32_bf16 v[98:101], v[168:171], v[192:195], v[98:101]
	v_mfma_f32_16x16x32_bf16 v[86:89], v[156:159], v[200:203], v[86:89]
	v_mfma_f32_16x16x32_bf16 v[82:85], v[168:171], v[200:203], v[82:85]
	s_barrier
	s_add_i32 s55, s47, s34
	s_add_u32 s96, s26, 0x80
	s_addc_u32 s97, s27, 0
	s_mov_b32 m0, s55
	s_nop 0
	global_load_lds_dwordx4 v130, s[26:27]
	s_add_i32 m0, s55, 0x2000
	s_nop 0
	global_load_lds_dwordx4 v132, s[26:27]
	s_waitcnt vmcnt(10)
	s_barrier
	s_waitcnt lgkmcnt(0)
	v_mfma_f32_16x16x32_bf16 v[110:113], v[204:207], v[172:175], 0
	ds_read_b128 v[224:227], v150 offset:16384
	v_mfma_f32_16x16x32_bf16 v[106:109], v[212:215], v[172:175], 0
	v_mfma_f32_16x16x32_bf16 v[94:97], v[204:207], v[180:183], 0
	ds_read_b128 v[228:231], v150 offset:17408
	v_mfma_f32_16x16x32_bf16 v[90:93], v[212:215], v[180:183], 0
	v_mfma_f32_16x16x32_bf16 v[78:81], v[204:207], v[188:191], 0
	ds_read_b128 v[232:235], v150 offset:18432
	v_mfma_f32_16x16x32_bf16 v[74:77], v[212:215], v[188:191], 0
	v_mfma_f32_16x16x32_bf16 v[70:73], v[204:207], v[196:199], 0
	ds_read_b128 v[236:239], v150 offset:19456
	v_mfma_f32_16x16x32_bf16 v[66:69], v[212:215], v[196:199], 0
	v_mfma_f32_16x16x32_bf16 v[110:113], v[208:211], v[176:179], v[110:113]
	ds_read_b128 v[240:243], v150 offset:20480
	v_mfma_f32_16x16x32_bf16 v[106:109], v[216:219], v[176:179], v[106:109]
	v_mfma_f32_16x16x32_bf16 v[94:97], v[208:211], v[184:187], v[94:97]
	ds_read_b128 v[244:247], v150 offset:21504
	v_mfma_f32_16x16x32_bf16 v[90:93], v[216:219], v[184:187], v[90:93]
	v_mfma_f32_16x16x32_bf16 v[78:81], v[208:211], v[192:195], v[78:81]
	ds_read_b128 v[248:251], v150 offset:22528
	v_mfma_f32_16x16x32_bf16 v[74:77], v[216:219], v[192:195], v[74:77]
	v_mfma_f32_16x16x32_bf16 v[70:73], v[208:211], v[200:203], v[70:73]
	ds_read_b128 v[164:167], v150 offset:23552
	v_mfma_f32_16x16x32_bf16 v[66:69], v[216:219], v[200:203], v[66:69]
	s_barrier
	s_mov_b32 m0, s39
	s_add_u32 s94, s28, 0x80
	s_addc_u32 s95, s29, 0
	global_load_lds_dwordx4 v130, s[28:29]
	s_mov_b32 m0, s40
	s_nop 0
	global_load_lds_dwordx4 v132, s[28:29]
	s_waitcnt vmcnt(8)
	s_barrier
	s_waitcnt lgkmcnt(0)
	v_mfma_f32_16x16x32_bf16 v[62:65], v[152:155], v[224:227], 0
	ds_read_b128 v[172:175], v150 offset:32768
	v_mfma_f32_16x16x32_bf16 v[58:61], v[160:163], v[224:227], 0
	v_mfma_f32_16x16x32_bf16 v[54:57], v[152:155], v[232:235], 0
	ds_read_b128 v[176:179], v150 offset:33792
	v_mfma_f32_16x16x32_bf16 v[50:53], v[160:163], v[232:235], 0
	v_mfma_f32_16x16x32_bf16 v[38:41], v[152:155], v[240:243], 0
	ds_read_b128 v[180:183], v150 offset:34816
	v_mfma_f32_16x16x32_bf16 v[34:37], v[160:163], v[240:243], 0
	v_mfma_f32_16x16x32_bf16 v[22:25], v[152:155], v[248:251], 0
	ds_read_b128 v[184:187], v150 offset:35840
	v_mfma_f32_16x16x32_bf16 v[18:21], v[160:163], v[248:251], 0
	v_mfma_f32_16x16x32_bf16 v[62:65], v[156:159], v[228:231], v[62:65]
	ds_read_b128 v[188:191], v150 offset:36864
	v_mfma_f32_16x16x32_bf16 v[58:61], v[168:171], v[228:231], v[58:61]
	v_mfma_f32_16x16x32_bf16 v[54:57], v[156:159], v[236:239], v[54:57]
	ds_read_b128 v[192:195], v150 offset:37888
	v_mfma_f32_16x16x32_bf16 v[50:53], v[168:171], v[236:239], v[50:53]
	v_mfma_f32_16x16x32_bf16 v[38:41], v[156:159], v[244:247], v[38:41]
	ds_read_b128 v[196:199], v150 offset:38912
	v_mfma_f32_16x16x32_bf16 v[34:37], v[168:171], v[244:247], v[34:37]
	v_mfma_f32_16x16x32_bf16 v[22:25], v[156:159], v[164:167], v[22:25]
	ds_read_b128 v[200:203], v150 offset:39936
	v_mfma_f32_16x16x32_bf16 v[18:21], v[168:171], v[164:167], v[18:21]
	s_barrier
	s_add_u32 s56, s26, 0x80000
	s_addc_u32 s57, s27, 0
	s_add_i32 s55, s48, s34
	s_mov_b32 m0, s55
	s_nop 0
	global_load_lds_dwordx4 v130, s[56:57]
	s_add_i32 m0, s55, 0x2000
	s_nop 0
	global_load_lds_dwordx4 v132, s[56:57]
	s_waitcnt vmcnt(10)
	s_barrier
	s_waitcnt lgkmcnt(0)
	v_mfma_f32_16x16x32_bf16 v[46:49], v[204:207], v[224:227], 0
	ds_read_b128 v[152:155], v222
	v_mfma_f32_16x16x32_bf16 v[42:45], v[212:215], v[224:227], 0
	v_mfma_f32_16x16x32_bf16 v[30:33], v[204:207], v[232:235], 0
	v_mfma_f32_16x16x32_bf16 v[26:29], v[212:215], v[232:235], 0
	v_mfma_f32_16x16x32_bf16 v[14:17], v[204:207], v[240:243], 0
	ds_read_b128 v[156:159], v222 offset:1024
	v_mfma_f32_16x16x32_bf16 v[10:13], v[212:215], v[240:243], 0
	v_mfma_f32_16x16x32_bf16 v[6:9], v[204:207], v[248:251], 0
	v_mfma_f32_16x16x32_bf16 v[2:5], v[212:215], v[248:251], 0
	v_mfma_f32_16x16x32_bf16 v[46:49], v[208:211], v[228:231], v[46:49]
	ds_read_b128 v[160:163], v222 offset:2048
	v_mfma_f32_16x16x32_bf16 v[42:45], v[216:219], v[228:231], v[42:45]
	v_mfma_f32_16x16x32_bf16 v[30:33], v[208:211], v[236:239], v[30:33]
	v_mfma_f32_16x16x32_bf16 v[26:29], v[216:219], v[236:239], v[26:29]
	v_mfma_f32_16x16x32_bf16 v[14:17], v[208:211], v[244:247], v[14:17]
	ds_read_b128 v[168:171], v222 offset:3072
	v_mfma_f32_16x16x32_bf16 v[10:13], v[216:219], v[244:247], v[10:13]
	v_mfma_f32_16x16x32_bf16 v[6:9], v[208:211], v[164:167], v[6:9]
	v_mfma_f32_16x16x32_bf16 v[2:5], v[216:219], v[164:167], v[2:5]
	s_barrier
	s_add_i32 s55, 0, 0x18000
	s_add_u32 s28, s28, 0x80000
	s_addc_u32 s29, s29, 0
	s_mov_b32 m0, s41
	s_nop 0
	global_load_lds_dwordx4 v130, s[28:29]
	s_mov_b32 m0, s42
	s_nop 0
	global_load_lds_dwordx4 v132, s[28:29]
	s_waitcnt vmcnt(10)
	s_barrier
	s_waitcnt lgkmcnt(0)
	v_mfma_f32_16x16x32_bf16 v[126:129], v[152:155], v[172:175], v[126:129]
	ds_read_b128 v[204:207], v223
	v_mfma_f32_16x16x32_bf16 v[122:125], v[160:163], v[172:175], v[122:125]
	v_mfma_f32_16x16x32_bf16 v[118:121], v[152:155], v[180:183], v[118:121]
	v_mfma_f32_16x16x32_bf16 v[114:117], v[160:163], v[180:183], v[114:117]
	v_mfma_f32_16x16x32_bf16 v[102:105], v[152:155], v[188:191], v[102:105]
	ds_read_b128 v[208:211], v223 offset:1024
	v_mfma_f32_16x16x32_bf16 v[98:101], v[160:163], v[188:191], v[98:101]
	v_mfma_f32_16x16x32_bf16 v[86:89], v[152:155], v[196:199], v[86:89]
	v_mfma_f32_16x16x32_bf16 v[82:85], v[160:163], v[196:199], v[82:85]
	v_mfma_f32_16x16x32_bf16 v[126:129], v[156:159], v[176:179], v[126:129]
	ds_read_b128 v[212:215], v223 offset:2048
	v_mfma_f32_16x16x32_bf16 v[122:125], v[168:171], v[176:179], v[122:125]
	v_mfma_f32_16x16x32_bf16 v[118:121], v[156:159], v[184:187], v[118:121]
	v_mfma_f32_16x16x32_bf16 v[114:117], v[168:171], v[184:187], v[114:117]
	v_mfma_f32_16x16x32_bf16 v[102:105], v[156:159], v[192:195], v[102:105]
	ds_read_b128 v[216:219], v223 offset:3072
	v_mfma_f32_16x16x32_bf16 v[98:101], v[168:171], v[192:195], v[98:101]
	v_mfma_f32_16x16x32_bf16 v[86:89], v[156:159], v[200:203], v[86:89]
	v_mfma_f32_16x16x32_bf16 v[82:85], v[168:171], v[200:203], v[82:85]
	s_barrier
	s_add_i32 s84, 0, 0x1c000
	s_add_i32 s85, s55, s34
	s_mov_b32 m0, s85
	s_nop 0
	global_load_lds_dwordx4 v130, s[96:97]
	s_add_i32 m0, s85, 0x2000
	s_nop 0
	global_load_lds_dwordx4 v132, s[96:97]
	s_waitcnt vmcnt(10)
	s_barrier
	s_waitcnt lgkmcnt(0)
	v_mfma_f32_16x16x32_bf16 v[110:113], v[204:207], v[172:175], v[110:113]
	ds_read_b128 v[224:227], v150 offset:49152
	v_mfma_f32_16x16x32_bf16 v[106:109], v[212:215], v[172:175], v[106:109]
	v_mfma_f32_16x16x32_bf16 v[94:97], v[204:207], v[180:183], v[94:97]
	ds_read_b128 v[228:231], v150 offset:50176
	v_mfma_f32_16x16x32_bf16 v[90:93], v[212:215], v[180:183], v[90:93]
	v_mfma_f32_16x16x32_bf16 v[78:81], v[204:207], v[188:191], v[78:81]
	ds_read_b128 v[232:235], v150 offset:51200
	v_mfma_f32_16x16x32_bf16 v[74:77], v[212:215], v[188:191], v[74:77]
	v_mfma_f32_16x16x32_bf16 v[70:73], v[204:207], v[196:199], v[70:73]
	ds_read_b128 v[236:239], v150 offset:52224
	v_mfma_f32_16x16x32_bf16 v[66:69], v[212:215], v[196:199], v[66:69]
	v_mfma_f32_16x16x32_bf16 v[110:113], v[208:211], v[176:179], v[110:113]
	ds_read_b128 v[240:243], v150 offset:53248
	v_mfma_f32_16x16x32_bf16 v[106:109], v[216:219], v[176:179], v[106:109]
	v_mfma_f32_16x16x32_bf16 v[94:97], v[208:211], v[184:187], v[94:97]
	ds_read_b128 v[244:247], v150 offset:54272
	v_mfma_f32_16x16x32_bf16 v[90:93], v[216:219], v[184:187], v[90:93]
	v_mfma_f32_16x16x32_bf16 v[78:81], v[208:211], v[192:195], v[78:81]
	ds_read_b128 v[248:251], v150 offset:55296
	v_mfma_f32_16x16x32_bf16 v[74:77], v[216:219], v[192:195], v[74:77]
	v_mfma_f32_16x16x32_bf16 v[70:73], v[208:211], v[200:203], v[70:73]
	ds_read_b128 v[164:167], v150 offset:56320
	v_mfma_f32_16x16x32_bf16 v[66:69], v[216:219], v[200:203], v[66:69]
	s_barrier
	s_mov_b32 m0, s45
	s_nop 0
	global_load_lds_dwordx4 v130, s[94:95]
	s_mov_b32 m0, s46
	s_nop 0
	global_load_lds_dwordx4 v132, s[94:95]
	s_waitcnt vmcnt(8)
	s_barrier
	s_waitcnt lgkmcnt(0)
	v_mfma_f32_16x16x32_bf16 v[62:65], v[152:155], v[224:227], v[62:65]
	ds_read_b128 v[172:175], v150
	v_mfma_f32_16x16x32_bf16 v[58:61], v[160:163], v[224:227], v[58:61]
	v_mfma_f32_16x16x32_bf16 v[54:57], v[152:155], v[232:235], v[54:57]
	ds_read_b128 v[176:179], v150 offset:1024
	v_mfma_f32_16x16x32_bf16 v[50:53], v[160:163], v[232:235], v[50:53]
	v_mfma_f32_16x16x32_bf16 v[38:41], v[152:155], v[240:243], v[38:41]
	ds_read_b128 v[180:183], v150 offset:2048
	v_mfma_f32_16x16x32_bf16 v[34:37], v[160:163], v[240:243], v[34:37]
	v_mfma_f32_16x16x32_bf16 v[22:25], v[152:155], v[248:251], v[22:25]
	ds_read_b128 v[184:187], v150 offset:3072
	v_mfma_f32_16x16x32_bf16 v[18:21], v[160:163], v[248:251], v[18:21]
	v_mfma_f32_16x16x32_bf16 v[62:65], v[156:159], v[228:231], v[62:65]
	ds_read_b128 v[188:191], v150 offset:4096
	v_mfma_f32_16x16x32_bf16 v[58:61], v[168:171], v[228:231], v[58:61]
	v_mfma_f32_16x16x32_bf16 v[54:57], v[156:159], v[236:239], v[54:57]
	ds_read_b128 v[192:195], v150 offset:5120
	v_mfma_f32_16x16x32_bf16 v[50:53], v[168:171], v[236:239], v[50:53]
	v_mfma_f32_16x16x32_bf16 v[38:41], v[156:159], v[244:247], v[38:41]
	ds_read_b128 v[196:199], v150 offset:6144
	v_mfma_f32_16x16x32_bf16 v[34:37], v[168:171], v[244:247], v[34:37]
	v_mfma_f32_16x16x32_bf16 v[22:25], v[156:159], v[164:167], v[22:25]
	ds_read_b128 v[200:203], v150 offset:7168
	v_mfma_f32_16x16x32_bf16 v[18:21], v[168:171], v[164:167], v[18:21]
	s_barrier
	s_add_u32 s26, s26, 0x80080
	s_addc_u32 s27, s27, 0
	s_add_i32 s84, s84, s34
	s_mov_b32 m0, s84
	s_nop 0
	global_load_lds_dwordx4 v130, s[26:27]
	s_add_i32 m0, s84, 0x2000
	s_nop 0
	global_load_lds_dwordx4 v132, s[26:27]
	s_waitcnt vmcnt(10)
	s_barrier
	s_waitcnt lgkmcnt(0)
	v_mfma_f32_16x16x32_bf16 v[46:49], v[204:207], v[224:227], v[46:49]
	ds_read_b128 v[152:155], v149
	v_mfma_f32_16x16x32_bf16 v[42:45], v[212:215], v[224:227], v[42:45]
	v_mfma_f32_16x16x32_bf16 v[30:33], v[204:207], v[232:235], v[30:33]
	v_mfma_f32_16x16x32_bf16 v[26:29], v[212:215], v[232:235], v[26:29]
	v_mfma_f32_16x16x32_bf16 v[14:17], v[204:207], v[240:243], v[14:17]
	ds_read_b128 v[156:159], v149 offset:1024
	v_mfma_f32_16x16x32_bf16 v[10:13], v[212:215], v[240:243], v[10:13]
	v_mfma_f32_16x16x32_bf16 v[6:9], v[204:207], v[248:251], v[6:9]
	v_mfma_f32_16x16x32_bf16 v[2:5], v[212:215], v[248:251], v[2:5]
	v_mfma_f32_16x16x32_bf16 v[46:49], v[208:211], v[228:231], v[46:49]
	ds_read_b128 v[160:163], v149 offset:2048
	v_mfma_f32_16x16x32_bf16 v[42:45], v[216:219], v[228:231], v[42:45]
	v_mfma_f32_16x16x32_bf16 v[30:33], v[208:211], v[236:239], v[30:33]
	v_mfma_f32_16x16x32_bf16 v[26:29], v[216:219], v[236:239], v[26:29]
	v_mfma_f32_16x16x32_bf16 v[14:17], v[208:211], v[244:247], v[14:17]
	ds_read_b128 v[168:171], v149 offset:3072
	v_mfma_f32_16x16x32_bf16 v[10:13], v[216:219], v[244:247], v[10:13]
	v_mfma_f32_16x16x32_bf16 v[6:9], v[208:211], v[164:167], v[6:9]
	v_mfma_f32_16x16x32_bf16 v[2:5], v[216:219], v[164:167], v[2:5]
	s_add_i32 s54, s54, 2
	s_add_u32 s24, s24, 0x100
	s_addc_u32 s25, s25, 0
	s_add_u32 s52, s52, 0x100
	s_addc_u32 s53, s53, 0
	s_cmp_gt_u32 s54, 29
	s_cbranch_scc0 .LBB0_377
	s_barrier
	s_branch .Lp2_loop_exit
.LBB0_377:
	s_barrier
	s_add_u32 s26, s24, 0xfff80080
	s_addc_u32 s27, s25, -1
	s_cmp_eq_u32 s54, 28
	s_cselect_b32 s29, s17, s27
	s_cselect_b32 s28, s19, s26
	s_cselect_b32 s27, s15, s53
	s_cselect_b32 s26, s51, s52
	s_add_i32 m0, s39, 0xc000
	s_nop 0
	global_load_lds_dwordx4 v136, s[24:25]
	s_add_i32 m0, s39, 0xe000
	s_nop 0
	global_load_lds_dwordx4 v138, s[24:25]
	s_waitcnt vmcnt(10)
	s_barrier
	s_waitcnt lgkmcnt(0)
	v_mfma_f32_16x16x32_bf16 v[126:129], v[152:155], v[172:175], v[126:129]
	ds_read_b128 v[204:207], v151
	v_mfma_f32_16x16x32_bf16 v[122:125], v[160:163], v[172:175], v[122:125]
	v_mfma_f32_16x16x32_bf16 v[118:121], v[152:155], v[180:183], v[118:121]
	v_mfma_f32_16x16x32_bf16 v[114:117], v[160:163], v[180:183], v[114:117]
	v_mfma_f32_16x16x32_bf16 v[102:105], v[152:155], v[188:191], v[102:105]
	ds_read_b128 v[208:211], v151 offset:1024
	v_mfma_f32_16x16x32_bf16 v[98:101], v[160:163], v[188:191], v[98:101]
	v_mfma_f32_16x16x32_bf16 v[86:89], v[152:155], v[196:199], v[86:89]
	v_mfma_f32_16x16x32_bf16 v[82:85], v[160:163], v[196:199], v[82:85]
	v_mfma_f32_16x16x32_bf16 v[126:129], v[156:159], v[176:179], v[126:129]
	ds_read_b128 v[212:215], v151 offset:2048
	v_mfma_f32_16x16x32_bf16 v[122:125], v[168:171], v[176:179], v[122:125]
	v_mfma_f32_16x16x32_bf16 v[118:121], v[156:159], v[184:187], v[118:121]
	v_mfma_f32_16x16x32_bf16 v[114:117], v[168:171], v[184:187], v[114:117]
	v_mfma_f32_16x16x32_bf16 v[102:105], v[156:159], v[192:195], v[102:105]
	ds_read_b128 v[216:219], v151 offset:3072
	v_mfma_f32_16x16x32_bf16 v[98:101], v[168:171], v[192:195], v[98:101]
	v_mfma_f32_16x16x32_bf16 v[86:89], v[156:159], v[200:203], v[86:89]
	v_mfma_f32_16x16x32_bf16 v[82:85], v[168:171], v[200:203], v[82:85]
	s_barrier
	s_add_i32 s55, s47, s34
	s_add_u32 s96, s26, 0x80
	s_addc_u32 s97, s27, 0
	s_mov_b32 m0, s55
	s_nop 0
	global_load_lds_dwordx4 v130, s[26:27]
	s_add_i32 m0, s55, 0x2000
	s_nop 0
	global_load_lds_dwordx4 v132, s[26:27]
	s_waitcnt vmcnt(10)
	s_barrier
	s_waitcnt lgkmcnt(0)
	v_mfma_f32_16x16x32_bf16 v[110:113], v[204:207], v[172:175], v[110:113]
	ds_read_b128 v[224:227], v150 offset:16384
	v_mfma_f32_16x16x32_bf16 v[106:109], v[212:215], v[172:175], v[106:109]
	v_mfma_f32_16x16x32_bf16 v[94:97], v[204:207], v[180:183], v[94:97]
	ds_read_b128 v[228:231], v150 offset:17408
	v_mfma_f32_16x16x32_bf16 v[90:93], v[212:215], v[180:183], v[90:93]
	v_mfma_f32_16x16x32_bf16 v[78:81], v[204:207], v[188:191], v[78:81]
	ds_read_b128 v[232:235], v150 offset:18432
	v_mfma_f32_16x16x32_bf16 v[74:77], v[212:215], v[188:191], v[74:77]
	v_mfma_f32_16x16x32_bf16 v[70:73], v[204:207], v[196:199], v[70:73]
	ds_read_b128 v[236:239], v150 offset:19456
	v_mfma_f32_16x16x32_bf16 v[66:69], v[212:215], v[196:199], v[66:69]
	v_mfma_f32_16x16x32_bf16 v[110:113], v[208:211], v[176:179], v[110:113]
	ds_read_b128 v[240:243], v150 offset:20480
	v_mfma_f32_16x16x32_bf16 v[106:109], v[216:219], v[176:179], v[106:109]
	v_mfma_f32_16x16x32_bf16 v[94:97], v[208:211], v[184:187], v[94:97]
	ds_read_b128 v[244:247], v150 offset:21504
	v_mfma_f32_16x16x32_bf16 v[90:93], v[216:219], v[184:187], v[90:93]
	v_mfma_f32_16x16x32_bf16 v[78:81], v[208:211], v[192:195], v[78:81]
	ds_read_b128 v[248:251], v150 offset:22528
	v_mfma_f32_16x16x32_bf16 v[74:77], v[216:219], v[192:195], v[74:77]
	v_mfma_f32_16x16x32_bf16 v[70:73], v[208:211], v[200:203], v[70:73]
	ds_read_b128 v[164:167], v150 offset:23552
	v_mfma_f32_16x16x32_bf16 v[66:69], v[216:219], v[200:203], v[66:69]
	s_barrier
	s_mov_b32 m0, s39
	s_add_u32 s94, s28, 0x80
	s_addc_u32 s95, s29, 0
	global_load_lds_dwordx4 v130, s[28:29]
	s_mov_b32 m0, s40
	s_nop 0
	global_load_lds_dwordx4 v132, s[28:29]
	s_waitcnt vmcnt(8)
	s_barrier
	s_waitcnt lgkmcnt(0)
	v_mfma_f32_16x16x32_bf16 v[62:65], v[152:155], v[224:227], v[62:65]
	ds_read_b128 v[172:175], v150 offset:32768
	v_mfma_f32_16x16x32_bf16 v[58:61], v[160:163], v[224:227], v[58:61]
	v_mfma_f32_16x16x32_bf16 v[54:57], v[152:155], v[232:235], v[54:57]
	ds_read_b128 v[176:179], v150 offset:33792
	v_mfma_f32_16x16x32_bf16 v[50:53], v[160:163], v[232:235], v[50:53]
	v_mfma_f32_16x16x32_bf16 v[38:41], v[152:155], v[240:243], v[38:41]
	ds_read_b128 v[180:183], v150 offset:34816
	v_mfma_f32_16x16x32_bf16 v[34:37], v[160:163], v[240:243], v[34:37]
	v_mfma_f32_16x16x32_bf16 v[22:25], v[152:155], v[248:251], v[22:25]
	ds_read_b128 v[184:187], v150 offset:35840
	v_mfma_f32_16x16x32_bf16 v[18:21], v[160:163], v[248:251], v[18:21]
	v_mfma_f32_16x16x32_bf16 v[62:65], v[156:159], v[228:231], v[62:65]
	ds_read_b128 v[188:191], v150 offset:36864
	v_mfma_f32_16x16x32_bf16 v[58:61], v[168:171], v[228:231], v[58:61]
	v_mfma_f32_16x16x32_bf16 v[54:57], v[156:159], v[236:239], v[54:57]
	ds_read_b128 v[192:195], v150 offset:37888
	v_mfma_f32_16x16x32_bf16 v[50:53], v[168:171], v[236:239], v[50:53]
	v_mfma_f32_16x16x32_bf16 v[38:41], v[156:159], v[244:247], v[38:41]
	ds_read_b128 v[196:199], v150 offset:38912
	v_mfma_f32_16x16x32_bf16 v[34:37], v[168:171], v[244:247], v[34:37]
	v_mfma_f32_16x16x32_bf16 v[22:25], v[156:159], v[164:167], v[22:25]
	ds_read_b128 v[200:203], v150 offset:39936
	v_mfma_f32_16x16x32_bf16 v[18:21], v[168:171], v[164:167], v[18:21]
	s_barrier
	s_add_u32 s56, s26, 0x80000
	s_addc_u32 s57, s27, 0
	s_add_i32 s55, s48, s34
	s_mov_b32 m0, s55
	s_nop 0
	global_load_lds_dwordx4 v130, s[56:57]
	s_add_i32 m0, s55, 0x2000
	s_nop 0
	global_load_lds_dwordx4 v132, s[56:57]
	s_waitcnt vmcnt(10)
	s_barrier
	s_waitcnt lgkmcnt(0)
	v_mfma_f32_16x16x32_bf16 v[46:49], v[204:207], v[224:227], v[46:49]
	ds_read_b128 v[152:155], v222
	v_mfma_f32_16x16x32_bf16 v[42:45], v[212:215], v[224:227], v[42:45]
	v_mfma_f32_16x16x32_bf16 v[30:33], v[204:207], v[232:235], v[30:33]
	v_mfma_f32_16x16x32_bf16 v[26:29], v[212:215], v[232:235], v[26:29]
	v_mfma_f32_16x16x32_bf16 v[14:17], v[204:207], v[240:243], v[14:17]
	ds_read_b128 v[156:159], v222 offset:1024
	v_mfma_f32_16x16x32_bf16 v[10:13], v[212:215], v[240:243], v[10:13]
	v_mfma_f32_16x16x32_bf16 v[6:9], v[204:207], v[248:251], v[6:9]
	v_mfma_f32_16x16x32_bf16 v[2:5], v[212:215], v[248:251], v[2:5]
	v_mfma_f32_16x16x32_bf16 v[46:49], v[208:211], v[228:231], v[46:49]
	ds_read_b128 v[160:163], v222 offset:2048
	v_mfma_f32_16x16x32_bf16 v[42:45], v[216:219], v[228:231], v[42:45]
	v_mfma_f32_16x16x32_bf16 v[30:33], v[208:211], v[236:239], v[30:33]
	v_mfma_f32_16x16x32_bf16 v[26:29], v[216:219], v[236:239], v[26:29]
	v_mfma_f32_16x16x32_bf16 v[14:17], v[208:211], v[244:247], v[14:17]
	ds_read_b128 v[168:171], v222 offset:3072
	v_mfma_f32_16x16x32_bf16 v[10:13], v[216:219], v[244:247], v[10:13]
	v_mfma_f32_16x16x32_bf16 v[6:9], v[208:211], v[164:167], v[6:9]
	v_mfma_f32_16x16x32_bf16 v[2:5], v[216:219], v[164:167], v[2:5]
	s_barrier
	s_add_i32 s55, 0, 0x18000
	s_add_u32 s28, s28, 0x80000
	s_addc_u32 s29, s29, 0
	s_mov_b32 m0, s41
	s_nop 0
	global_load_lds_dwordx4 v130, s[28:29]
	s_mov_b32 m0, s42
	s_nop 0
	global_load_lds_dwordx4 v132, s[28:29]
	s_waitcnt vmcnt(10)
	s_barrier
	s_waitcnt lgkmcnt(0)
	v_mfma_f32_16x16x32_bf16 v[126:129], v[152:155], v[172:175], v[126:129]
	ds_read_b128 v[204:207], v223
	v_mfma_f32_16x16x32_bf16 v[122:125], v[160:163], v[172:175], v[122:125]
	v_mfma_f32_16x16x32_bf16 v[118:121], v[152:155], v[180:183], v[118:121]
	v_mfma_f32_16x16x32_bf16 v[114:117], v[160:163], v[180:183], v[114:117]
	v_mfma_f32_16x16x32_bf16 v[102:105], v[152:155], v[188:191], v[102:105]
	ds_read_b128 v[208:211], v223 offset:1024
	v_mfma_f32_16x16x32_bf16 v[98:101], v[160:163], v[188:191], v[98:101]
	v_mfma_f32_16x16x32_bf16 v[86:89], v[152:155], v[196:199], v[86:89]
	v_mfma_f32_16x16x32_bf16 v[82:85], v[160:163], v[196:199], v[82:85]
	v_mfma_f32_16x16x32_bf16 v[126:129], v[156:159], v[176:179], v[126:129]
	ds_read_b128 v[212:215], v223 offset:2048
	v_mfma_f32_16x16x32_bf16 v[122:125], v[168:171], v[176:179], v[122:125]
	v_mfma_f32_16x16x32_bf16 v[118:121], v[156:159], v[184:187], v[118:121]
	v_mfma_f32_16x16x32_bf16 v[114:117], v[168:171], v[184:187], v[114:117]
	v_mfma_f32_16x16x32_bf16 v[102:105], v[156:159], v[192:195], v[102:105]
	ds_read_b128 v[216:219], v223 offset:3072
	v_mfma_f32_16x16x32_bf16 v[98:101], v[168:171], v[192:195], v[98:101]
	v_mfma_f32_16x16x32_bf16 v[86:89], v[156:159], v[200:203], v[86:89]
	v_mfma_f32_16x16x32_bf16 v[82:85], v[168:171], v[200:203], v[82:85]
	s_barrier
	s_add_i32 s84, 0, 0x1c000
	s_add_i32 s85, s55, s34
	s_mov_b32 m0, s85
	s_nop 0
	global_load_lds_dwordx4 v130, s[96:97]
	s_add_i32 m0, s85, 0x2000
	s_nop 0
	global_load_lds_dwordx4 v132, s[96:97]
	s_waitcnt vmcnt(10)
	s_barrier
	s_waitcnt lgkmcnt(0)
	v_mfma_f32_16x16x32_bf16 v[110:113], v[204:207], v[172:175], v[110:113]
	ds_read_b128 v[224:227], v150 offset:49152
	v_mfma_f32_16x16x32_bf16 v[106:109], v[212:215], v[172:175], v[106:109]
	v_mfma_f32_16x16x32_bf16 v[94:97], v[204:207], v[180:183], v[94:97]
	ds_read_b128 v[228:231], v150 offset:50176
	v_mfma_f32_16x16x32_bf16 v[90:93], v[212:215], v[180:183], v[90:93]
	v_mfma_f32_16x16x32_bf16 v[78:81], v[204:207], v[188:191], v[78:81]
	ds_read_b128 v[232:235], v150 offset:51200
	v_mfma_f32_16x16x32_bf16 v[74:77], v[212:215], v[188:191], v[74:77]
	v_mfma_f32_16x16x32_bf16 v[70:73], v[204:207], v[196:199], v[70:73]
	ds_read_b128 v[236:239], v150 offset:52224
	v_mfma_f32_16x16x32_bf16 v[66:69], v[212:215], v[196:199], v[66:69]
	v_mfma_f32_16x16x32_bf16 v[110:113], v[208:211], v[176:179], v[110:113]
	ds_read_b128 v[240:243], v150 offset:53248
	v_mfma_f32_16x16x32_bf16 v[106:109], v[216:219], v[176:179], v[106:109]
	v_mfma_f32_16x16x32_bf16 v[94:97], v[208:211], v[184:187], v[94:97]
	ds_read_b128 v[244:247], v150 offset:54272
	v_mfma_f32_16x16x32_bf16 v[90:93], v[216:219], v[184:187], v[90:93]
	v_mfma_f32_16x16x32_bf16 v[78:81], v[208:211], v[192:195], v[78:81]
	ds_read_b128 v[248:251], v150 offset:55296
	v_mfma_f32_16x16x32_bf16 v[74:77], v[216:219], v[192:195], v[74:77]
	v_mfma_f32_16x16x32_bf16 v[70:73], v[208:211], v[200:203], v[70:73]
	ds_read_b128 v[164:167], v150 offset:56320
	v_mfma_f32_16x16x32_bf16 v[66:69], v[216:219], v[200:203], v[66:69]
	s_barrier
	s_mov_b32 m0, s45
	s_nop 0
	global_load_lds_dwordx4 v130, s[94:95]
	s_mov_b32 m0, s46
	s_nop 0
	global_load_lds_dwordx4 v132, s[94:95]
	s_waitcnt vmcnt(8)
	s_barrier
	s_waitcnt lgkmcnt(0)
	v_mfma_f32_16x16x32_bf16 v[62:65], v[152:155], v[224:227], v[62:65]
	ds_read_b128 v[172:175], v150
	v_mfma_f32_16x16x32_bf16 v[58:61], v[160:163], v[224:227], v[58:61]
	v_mfma_f32_16x16x32_bf16 v[54:57], v[152:155], v[232:235], v[54:57]
	ds_read_b128 v[176:179], v150 offset:1024
	v_mfma_f32_16x16x32_bf16 v[50:53], v[160:163], v[232:235], v[50:53]
	v_mfma_f32_16x16x32_bf16 v[38:41], v[152:155], v[240:243], v[38:41]
	ds_read_b128 v[180:183], v150 offset:2048
	v_mfma_f32_16x16x32_bf16 v[34:37], v[160:163], v[240:243], v[34:37]
	v_mfma_f32_16x16x32_bf16 v[22:25], v[152:155], v[248:251], v[22:25]
	ds_read_b128 v[184:187], v150 offset:3072
	v_mfma_f32_16x16x32_bf16 v[18:21], v[160:163], v[248:251], v[18:21]
	v_mfma_f32_16x16x32_bf16 v[62:65], v[156:159], v[228:231], v[62:65]
	ds_read_b128 v[188:191], v150 offset:4096
	v_mfma_f32_16x16x32_bf16 v[58:61], v[168:171], v[228:231], v[58:61]
	v_mfma_f32_16x16x32_bf16 v[54:57], v[156:159], v[236:239], v[54:57]
	ds_read_b128 v[192:195], v150 offset:5120
	v_mfma_f32_16x16x32_bf16 v[50:53], v[168:171], v[236:239], v[50:53]
	v_mfma_f32_16x16x32_bf16 v[38:41], v[156:159], v[244:247], v[38:41]
	ds_read_b128 v[196:199], v150 offset:6144
	v_mfma_f32_16x16x32_bf16 v[34:37], v[168:171], v[244:247], v[34:37]
	v_mfma_f32_16x16x32_bf16 v[22:25], v[156:159], v[164:167], v[22:25]
	ds_read_b128 v[200:203], v150 offset:7168
	v_mfma_f32_16x16x32_bf16 v[18:21], v[168:171], v[164:167], v[18:21]
	s_barrier
	s_add_u32 s26, s26, 0x80080
	s_addc_u32 s27, s27, 0
	s_add_i32 s84, s84, s34
	s_mov_b32 m0, s84
	s_nop 0
	global_load_lds_dwordx4 v130, s[26:27]
	s_add_i32 m0, s84, 0x2000
	s_nop 0
	global_load_lds_dwordx4 v132, s[26:27]
	s_waitcnt vmcnt(10)
	s_barrier
	s_waitcnt lgkmcnt(0)
	v_mfma_f32_16x16x32_bf16 v[46:49], v[204:207], v[224:227], v[46:49]
	ds_read_b128 v[152:155], v149
	v_mfma_f32_16x16x32_bf16 v[42:45], v[212:215], v[224:227], v[42:45]
	v_mfma_f32_16x16x32_bf16 v[30:33], v[204:207], v[232:235], v[30:33]
	v_mfma_f32_16x16x32_bf16 v[26:29], v[212:215], v[232:235], v[26:29]
	v_mfma_f32_16x16x32_bf16 v[14:17], v[204:207], v[240:243], v[14:17]
	ds_read_b128 v[156:159], v149 offset:1024
	v_mfma_f32_16x16x32_bf16 v[10:13], v[212:215], v[240:243], v[10:13]
	v_mfma_f32_16x16x32_bf16 v[6:9], v[204:207], v[248:251], v[6:9]
	v_mfma_f32_16x16x32_bf16 v[2:5], v[212:215], v[248:251], v[2:5]
	v_mfma_f32_16x16x32_bf16 v[46:49], v[208:211], v[228:231], v[46:49]
	ds_read_b128 v[160:163], v149 offset:2048
	v_mfma_f32_16x16x32_bf16 v[42:45], v[216:219], v[228:231], v[42:45]
	v_mfma_f32_16x16x32_bf16 v[30:33], v[208:211], v[236:239], v[30:33]
	v_mfma_f32_16x16x32_bf16 v[26:29], v[216:219], v[236:239], v[26:29]
	v_mfma_f32_16x16x32_bf16 v[14:17], v[208:211], v[244:247], v[14:17]
	ds_read_b128 v[168:171], v149 offset:3072
	v_mfma_f32_16x16x32_bf16 v[10:13], v[216:219], v[244:247], v[10:13]
	v_mfma_f32_16x16x32_bf16 v[6:9], v[208:211], v[164:167], v[6:9]
	v_mfma_f32_16x16x32_bf16 v[2:5], v[216:219], v[164:167], v[2:5]
	s_add_i32 s54, s54, 2
	s_add_u32 s24, s24, 0x100
	s_addc_u32 s25, s25, 0
	s_add_u32 s52, s52, 0x100
	s_addc_u32 s53, s53, 0
	s_cmp_gt_u32 s54, 29
	s_cbranch_scc0 .LBB0_377
	s_barrier

.LBB0_944:
	v_add_u32_e32 v158, 0x18000, v164
	v_add_u32_e32 v159, 0x1c000, v164
	ds_read_b128 v[130:133], v167
	ds_read_b128 v[134:137], v167 offset:1024
	ds_read_b128 v[138:141], v167 offset:2048
	ds_read_b128 v[142:145], v167 offset:3072
	ds_read_b128 v[172:175], v170
	ds_read_b128 v[176:179], v170 offset:1024
	ds_read_b128 v[180:183], v170 offset:2048
	ds_read_b128 v[184:187], v170 offset:3072
	ds_read_b128 v[188:191], v170 offset:4096
	ds_read_b128 v[192:195], v170 offset:5120
	ds_read_b128 v[196:199], v170 offset:6144
	ds_read_b128 v[200:203], v170 offset:7168
	s_ashr_i32 s29, s28, 31
	v_cmp_lt_i64_e32 vcc, s[30:31], v[154:155]
	s_lshl_b64 s[30:31], s[28:29], 20
	s_add_u32 s30, s48, s30
	s_addc_u32 s31, s49, s31
	s_and_b64 s[34:35], vcc, exec
	s_cselect_b32 s29, s31, s39
	s_cselect_b32 s63, s30, s38
	s_ashr_i32 s27, s26, 31
	s_lshl_b64 s[34:35], s[26:27], 20
	s_add_u32 s34, s54, s34
	s_addc_u32 s35, s55, s35
	s_and_b64 s[42:43], vcc, exec
	s_cselect_b32 s27, s35, s41
	s_cselect_b32 s64, s34, s40
	s_add_u32 s38, s38, 0x80080
	s_addc_u32 s39, s39, 0
	s_add_u32 s65, s40, 0x100
	s_addc_u32 s66, s41, 0
	s_mov_b32 s67, -2
	s_add_u32 s40, s38, 0xfff80080
	s_addc_u32 s41, s39, -1
	s_cmp_eq_u32 s67, 28
	s_cselect_b32 s43, s29, s41
	s_cselect_b32 s42, s63, s40
	s_cselect_b32 s41, s27, s66
	s_cselect_b32 s40, s64, s65
	s_add_i32 m0, s37, 0xc000
	s_nop 0
	global_load_lds_dwordx4 v150, s[38:39]
	s_add_i32 m0, s37, 0xe000
	s_nop 0
	global_load_lds_dwordx4 v152, s[38:39]
	s_waitcnt vmcnt(10)
	s_barrier
	s_waitcnt lgkmcnt(0)
	v_mfma_f32_16x16x32_bf16 v[126:129], v[130:133], v[172:175], 0
	ds_read_b128 v[204:207], v171
	v_mfma_f32_16x16x32_bf16 v[122:125], v[138:141], v[172:175], 0
	v_mfma_f32_16x16x32_bf16 v[114:117], v[130:133], v[180:183], 0
	v_mfma_f32_16x16x32_bf16 v[106:109], v[138:141], v[180:183], 0
	v_mfma_f32_16x16x32_bf16 v[98:101], v[130:133], v[188:191], 0
	ds_read_b128 v[208:211], v171 offset:1024
	v_mfma_f32_16x16x32_bf16 v[90:93], v[138:141], v[188:191], 0
	v_mfma_f32_16x16x32_bf16 v[82:85], v[130:133], v[196:199], 0
	v_mfma_f32_16x16x32_bf16 v[74:77], v[138:141], v[196:199], 0
	v_mfma_f32_16x16x32_bf16 v[126:129], v[134:137], v[176:179], v[126:129]
	ds_read_b128 v[212:215], v171 offset:2048
	v_mfma_f32_16x16x32_bf16 v[122:125], v[142:145], v[176:179], v[122:125]
	v_mfma_f32_16x16x32_bf16 v[114:117], v[134:137], v[184:187], v[114:117]
	v_mfma_f32_16x16x32_bf16 v[106:109], v[142:145], v[184:187], v[106:109]
	v_mfma_f32_16x16x32_bf16 v[98:101], v[134:137], v[192:195], v[98:101]
	ds_read_b128 v[216:219], v171 offset:3072
	v_mfma_f32_16x16x32_bf16 v[90:93], v[142:145], v[192:195], v[90:93]
	v_mfma_f32_16x16x32_bf16 v[82:85], v[134:137], v[200:203], v[82:85]
	v_mfma_f32_16x16x32_bf16 v[74:77], v[142:145], v[200:203], v[74:77]
	s_barrier
	s_add_i32 s68, s59, s47
	s_add_u32 s96, s40, 0x80
	s_addc_u32 s97, s41, 0
	s_mov_b32 m0, s68
	s_nop 0
	global_load_lds_dwordx4 v146, s[40:41]
	s_add_i32 m0, s68, 0x2000
	s_nop 0
	global_load_lds_dwordx4 v148, s[40:41]
	s_waitcnt vmcnt(10)
	s_barrier
	s_waitcnt lgkmcnt(0)
	v_mfma_f32_16x16x32_bf16 v[118:121], v[204:207], v[172:175], 0
	ds_read_b128 v[224:227], v170 offset:16384
	v_mfma_f32_16x16x32_bf16 v[110:113], v[212:215], v[172:175], 0
	v_mfma_f32_16x16x32_bf16 v[102:105], v[204:207], v[180:183], 0
	ds_read_b128 v[228:231], v170 offset:17408
	v_mfma_f32_16x16x32_bf16 v[94:97], v[212:215], v[180:183], 0
	v_mfma_f32_16x16x32_bf16 v[86:89], v[204:207], v[188:191], 0
	ds_read_b128 v[232:235], v170 offset:18432
	v_mfma_f32_16x16x32_bf16 v[78:81], v[212:215], v[188:191], 0
	v_mfma_f32_16x16x32_bf16 v[70:73], v[204:207], v[196:199], 0
	ds_read_b128 v[236:239], v170 offset:19456
	v_mfma_f32_16x16x32_bf16 v[66:69], v[212:215], v[196:199], 0
	v_mfma_f32_16x16x32_bf16 v[118:121], v[208:211], v[176:179], v[118:121]
	ds_read_b128 v[240:243], v170 offset:20480
	v_mfma_f32_16x16x32_bf16 v[110:113], v[216:219], v[176:179], v[110:113]
	v_mfma_f32_16x16x32_bf16 v[102:105], v[208:211], v[184:187], v[102:105]
	ds_read_b128 v[244:247], v170 offset:21504
	v_mfma_f32_16x16x32_bf16 v[94:97], v[216:219], v[184:187], v[94:97]
	v_mfma_f32_16x16x32_bf16 v[86:89], v[208:211], v[192:195], v[86:89]
	ds_read_b128 v[248:251], v170 offset:22528
	v_mfma_f32_16x16x32_bf16 v[78:81], v[216:219], v[192:195], v[78:81]
	v_mfma_f32_16x16x32_bf16 v[70:73], v[208:211], v[200:203], v[70:73]
	ds_read_b128 v[220:223], v170 offset:23552
	v_mfma_f32_16x16x32_bf16 v[66:69], v[216:219], v[200:203], v[66:69]
	s_barrier
	s_mov_b32 m0, s37
	s_add_u32 s94, s42, 0x80
	s_addc_u32 s95, s43, 0
	global_load_lds_dwordx4 v146, s[42:43]
	s_mov_b32 m0, s50
	s_nop 0
	global_load_lds_dwordx4 v148, s[42:43]
	s_waitcnt vmcnt(8)
	s_barrier
	s_waitcnt lgkmcnt(0)
	v_mfma_f32_16x16x32_bf16 v[62:65], v[130:133], v[224:227], 0
	ds_read_b128 v[172:175], v170 offset:32768
	v_mfma_f32_16x16x32_bf16 v[58:61], v[138:141], v[224:227], 0
	v_mfma_f32_16x16x32_bf16 v[54:57], v[130:133], v[232:235], 0
	ds_read_b128 v[176:179], v170 offset:33792
	v_mfma_f32_16x16x32_bf16 v[46:49], v[138:141], v[232:235], 0
	v_mfma_f32_16x16x32_bf16 v[38:41], v[130:133], v[240:243], 0
	ds_read_b128 v[180:183], v170 offset:34816
	v_mfma_f32_16x16x32_bf16 v[30:33], v[138:141], v[240:243], 0
	v_mfma_f32_16x16x32_bf16 v[22:25], v[130:133], v[248:251], 0
	ds_read_b128 v[184:187], v170 offset:35840
	v_mfma_f32_16x16x32_bf16 v[14:17], v[138:141], v[248:251], 0
	v_mfma_f32_16x16x32_bf16 v[62:65], v[134:137], v[228:231], v[62:65]
	ds_read_b128 v[188:191], v170 offset:36864
	v_mfma_f32_16x16x32_bf16 v[58:61], v[142:145], v[228:231], v[58:61]
	v_mfma_f32_16x16x32_bf16 v[54:57], v[134:137], v[236:239], v[54:57]
	ds_read_b128 v[192:195], v170 offset:37888
	v_mfma_f32_16x16x32_bf16 v[46:49], v[142:145], v[236:239], v[46:49]
	v_mfma_f32_16x16x32_bf16 v[38:41], v[134:137], v[244:247], v[38:41]
	ds_read_b128 v[196:199], v170 offset:38912
	v_mfma_f32_16x16x32_bf16 v[30:33], v[142:145], v[244:247], v[30:33]
	v_mfma_f32_16x16x32_bf16 v[22:25], v[134:137], v[220:223], v[22:25]
	ds_read_b128 v[200:203], v170 offset:39936
	v_mfma_f32_16x16x32_bf16 v[14:17], v[142:145], v[220:223], v[14:17]
	s_barrier
	s_add_u32 s68, s40, 0x80000
	s_addc_u32 s69, s41, 0
	s_add_i32 s70, s60, s47
	s_mov_b32 m0, s70
	s_nop 0
	global_load_lds_dwordx4 v146, s[68:69]
	s_add_i32 m0, s70, 0x2000
	s_nop 0
	global_load_lds_dwordx4 v148, s[68:69]
	s_waitcnt vmcnt(10)
	s_barrier
	s_waitcnt lgkmcnt(0)
	v_mfma_f32_16x16x32_bf16 v[50:53], v[204:207], v[224:227], 0
	ds_read_b128 v[130:133], v158
	v_mfma_f32_16x16x32_bf16 v[42:45], v[212:215], v[224:227], 0
	v_mfma_f32_16x16x32_bf16 v[34:37], v[204:207], v[232:235], 0
	v_mfma_f32_16x16x32_bf16 v[26:29], v[212:215], v[232:235], 0
	v_mfma_f32_16x16x32_bf16 v[18:21], v[204:207], v[240:243], 0
	ds_read_b128 v[134:137], v158 offset:1024
	v_mfma_f32_16x16x32_bf16 v[10:13], v[212:215], v[240:243], 0
	v_mfma_f32_16x16x32_bf16 v[6:9], v[204:207], v[248:251], 0
	v_mfma_f32_16x16x32_bf16 v[2:5], v[212:215], v[248:251], 0
	v_mfma_f32_16x16x32_bf16 v[50:53], v[208:211], v[228:231], v[50:53]
	ds_read_b128 v[138:141], v158 offset:2048
	v_mfma_f32_16x16x32_bf16 v[42:45], v[216:219], v[228:231], v[42:45]
	v_mfma_f32_16x16x32_bf16 v[34:37], v[208:211], v[236:239], v[34:37]
	v_mfma_f32_16x16x32_bf16 v[26:29], v[216:219], v[236:239], v[26:29]
	v_mfma_f32_16x16x32_bf16 v[18:21], v[208:211], v[244:247], v[18:21]
	ds_read_b128 v[142:145], v158 offset:3072
	v_mfma_f32_16x16x32_bf16 v[10:13], v[216:219], v[244:247], v[10:13]
	v_mfma_f32_16x16x32_bf16 v[6:9], v[208:211], v[220:223], v[6:9]
	v_mfma_f32_16x16x32_bf16 v[2:5], v[216:219], v[220:223], v[2:5]
	s_barrier
	s_add_i32 s70, 0, 0x18000
	s_add_u32 s42, s42, 0x80000
	s_addc_u32 s43, s43, 0
	s_mov_b32 m0, s51
	s_nop 0
	global_load_lds_dwordx4 v146, s[42:43]
	s_mov_b32 m0, s52
	s_nop 0
	global_load_lds_dwordx4 v148, s[42:43]
	s_waitcnt vmcnt(10)
	s_barrier
	s_waitcnt lgkmcnt(0)
	v_mfma_f32_16x16x32_bf16 v[126:129], v[130:133], v[172:175], v[126:129]
	ds_read_b128 v[204:207], v159
	v_mfma_f32_16x16x32_bf16 v[122:125], v[138:141], v[172:175], v[122:125]
	v_mfma_f32_16x16x32_bf16 v[114:117], v[130:133], v[180:183], v[114:117]
	v_mfma_f32_16x16x32_bf16 v[106:109], v[138:141], v[180:183], v[106:109]
	v_mfma_f32_16x16x32_bf16 v[98:101], v[130:133], v[188:191], v[98:101]
	ds_read_b128 v[208:211], v159 offset:1024
	v_mfma_f32_16x16x32_bf16 v[90:93], v[138:141], v[188:191], v[90:93]
	v_mfma_f32_16x16x32_bf16 v[82:85], v[130:133], v[196:199], v[82:85]
	v_mfma_f32_16x16x32_bf16 v[74:77], v[138:141], v[196:199], v[74:77]
	v_mfma_f32_16x16x32_bf16 v[126:129], v[134:137], v[176:179], v[126:129]
	ds_read_b128 v[212:215], v159 offset:2048
	v_mfma_f32_16x16x32_bf16 v[122:125], v[142:145], v[176:179], v[122:125]
	v_mfma_f32_16x16x32_bf16 v[114:117], v[134:137], v[184:187], v[114:117]
	v_mfma_f32_16x16x32_bf16 v[106:109], v[142:145], v[184:187], v[106:109]
	v_mfma_f32_16x16x32_bf16 v[98:101], v[134:137], v[192:195], v[98:101]
	ds_read_b128 v[216:219], v159 offset:3072
	v_mfma_f32_16x16x32_bf16 v[90:93], v[142:145], v[192:195], v[90:93]
	v_mfma_f32_16x16x32_bf16 v[82:85], v[134:137], v[200:203], v[82:85]
	v_mfma_f32_16x16x32_bf16 v[74:77], v[142:145], v[200:203], v[74:77]
	s_barrier
	s_add_i32 s84, 0, 0x1c000
	s_add_i32 s85, s70, s47
	s_mov_b32 m0, s85
	s_nop 0
	global_load_lds_dwordx4 v146, s[96:97]
	s_add_i32 m0, s85, 0x2000
	s_nop 0
	global_load_lds_dwordx4 v148, s[96:97]
	s_waitcnt vmcnt(10)
	s_barrier
	s_waitcnt lgkmcnt(0)
	v_mfma_f32_16x16x32_bf16 v[118:121], v[204:207], v[172:175], v[118:121]
	ds_read_b128 v[224:227], v170 offset:49152
	v_mfma_f32_16x16x32_bf16 v[110:113], v[212:215], v[172:175], v[110:113]
	v_mfma_f32_16x16x32_bf16 v[102:105], v[204:207], v[180:183], v[102:105]
	ds_read_b128 v[228:231], v170 offset:50176
	v_mfma_f32_16x16x32_bf16 v[94:97], v[212:215], v[180:183], v[94:97]
	v_mfma_f32_16x16x32_bf16 v[86:89], v[204:207], v[188:191], v[86:89]
	ds_read_b128 v[232:235], v170 offset:51200
	v_mfma_f32_16x16x32_bf16 v[78:81], v[212:215], v[188:191], v[78:81]
	v_mfma_f32_16x16x32_bf16 v[70:73], v[204:207], v[196:199], v[70:73]
	ds_read_b128 v[236:239], v170 offset:52224
	v_mfma_f32_16x16x32_bf16 v[66:69], v[212:215], v[196:199], v[66:69]
	v_mfma_f32_16x16x32_bf16 v[118:121], v[208:211], v[176:179], v[118:121]
	ds_read_b128 v[240:243], v170 offset:53248
	v_mfma_f32_16x16x32_bf16 v[110:113], v[216:219], v[176:179], v[110:113]
	v_mfma_f32_16x16x32_bf16 v[102:105], v[208:211], v[184:187], v[102:105]
	ds_read_b128 v[244:247], v170 offset:54272
	v_mfma_f32_16x16x32_bf16 v[94:97], v[216:219], v[184:187], v[94:97]
	v_mfma_f32_16x16x32_bf16 v[86:89], v[208:211], v[192:195], v[86:89]
	ds_read_b128 v[248:251], v170 offset:55296
	v_mfma_f32_16x16x32_bf16 v[78:81], v[216:219], v[192:195], v[78:81]
	v_mfma_f32_16x16x32_bf16 v[70:73], v[208:211], v[200:203], v[70:73]
	ds_read_b128 v[220:223], v170 offset:56320
	v_mfma_f32_16x16x32_bf16 v[66:69], v[216:219], v[200:203], v[66:69]
	s_barrier
	s_mov_b32 m0, s57
	s_nop 0
	global_load_lds_dwordx4 v146, s[94:95]
	s_mov_b32 m0, s58
	s_nop 0
	global_load_lds_dwordx4 v148, s[94:95]
	s_waitcnt vmcnt(8)
	s_barrier
	s_waitcnt lgkmcnt(0)
	v_mfma_f32_16x16x32_bf16 v[62:65], v[130:133], v[224:227], v[62:65]
	ds_read_b128 v[172:175], v170
	v_mfma_f32_16x16x32_bf16 v[58:61], v[138:141], v[224:227], v[58:61]
	v_mfma_f32_16x16x32_bf16 v[54:57], v[130:133], v[232:235], v[54:57]
	ds_read_b128 v[176:179], v170 offset:1024
	v_mfma_f32_16x16x32_bf16 v[46:49], v[138:141], v[232:235], v[46:49]
	v_mfma_f32_16x16x32_bf16 v[38:41], v[130:133], v[240:243], v[38:41]
	ds_read_b128 v[180:183], v170 offset:2048
	v_mfma_f32_16x16x32_bf16 v[30:33], v[138:141], v[240:243], v[30:33]
	v_mfma_f32_16x16x32_bf16 v[22:25], v[130:133], v[248:251], v[22:25]
	ds_read_b128 v[184:187], v170 offset:3072
	v_mfma_f32_16x16x32_bf16 v[14:17], v[138:141], v[248:251], v[14:17]
	v_mfma_f32_16x16x32_bf16 v[62:65], v[134:137], v[228:231], v[62:65]
	ds_read_b128 v[188:191], v170 offset:4096
	v_mfma_f32_16x16x32_bf16 v[58:61], v[142:145], v[228:231], v[58:61]
	v_mfma_f32_16x16x32_bf16 v[54:57], v[134:137], v[236:239], v[54:57]
	ds_read_b128 v[192:195], v170 offset:5120
	v_mfma_f32_16x16x32_bf16 v[46:49], v[142:145], v[236:239], v[46:49]
	v_mfma_f32_16x16x32_bf16 v[38:41], v[134:137], v[244:247], v[38:41]
	ds_read_b128 v[196:199], v170 offset:6144
	v_mfma_f32_16x16x32_bf16 v[30:33], v[142:145], v[244:247], v[30:33]
	v_mfma_f32_16x16x32_bf16 v[22:25], v[134:137], v[220:223], v[22:25]
	ds_read_b128 v[200:203], v170 offset:7168
	v_mfma_f32_16x16x32_bf16 v[14:17], v[142:145], v[220:223], v[14:17]
	s_barrier
	s_add_u32 s40, s40, 0x80080
	s_addc_u32 s41, s41, 0
	s_add_i32 s84, s84, s47
	s_mov_b32 m0, s84
	s_nop 0
	global_load_lds_dwordx4 v146, s[40:41]
	s_add_i32 m0, s84, 0x2000
	s_nop 0
	global_load_lds_dwordx4 v148, s[40:41]
	s_waitcnt vmcnt(10)
	s_barrier
	s_waitcnt lgkmcnt(0)
	v_mfma_f32_16x16x32_bf16 v[50:53], v[204:207], v[224:227], v[50:53]
	ds_read_b128 v[130:133], v167
	v_mfma_f32_16x16x32_bf16 v[42:45], v[212:215], v[224:227], v[42:45]
	v_mfma_f32_16x16x32_bf16 v[34:37], v[204:207], v[232:235], v[34:37]
	v_mfma_f32_16x16x32_bf16 v[26:29], v[212:215], v[232:235], v[26:29]
	v_mfma_f32_16x16x32_bf16 v[18:21], v[204:207], v[240:243], v[18:21]
	ds_read_b128 v[134:137], v167 offset:1024
	v_mfma_f32_16x16x32_bf16 v[10:13], v[212:215], v[240:243], v[10:13]
	v_mfma_f32_16x16x32_bf16 v[6:9], v[204:207], v[248:251], v[6:9]
	v_mfma_f32_16x16x32_bf16 v[2:5], v[212:215], v[248:251], v[2:5]
	v_mfma_f32_16x16x32_bf16 v[50:53], v[208:211], v[228:231], v[50:53]
	ds_read_b128 v[138:141], v167 offset:2048
	v_mfma_f32_16x16x32_bf16 v[42:45], v[216:219], v[228:231], v[42:45]
	v_mfma_f32_16x16x32_bf16 v[34:37], v[208:211], v[236:239], v[34:37]
	v_mfma_f32_16x16x32_bf16 v[26:29], v[216:219], v[236:239], v[26:29]
	v_mfma_f32_16x16x32_bf16 v[18:21], v[208:211], v[244:247], v[18:21]
	ds_read_b128 v[142:145], v167 offset:3072
	v_mfma_f32_16x16x32_bf16 v[10:13], v[216:219], v[244:247], v[10:13]
	v_mfma_f32_16x16x32_bf16 v[6:9], v[208:211], v[220:223], v[6:9]
	v_mfma_f32_16x16x32_bf16 v[2:5], v[216:219], v[220:223], v[2:5]
	s_add_i32 s67, s67, 2
	s_add_u32 s38, s38, 0x100
	s_addc_u32 s39, s39, 0
	s_add_u32 s65, s65, 0x100
	s_addc_u32 s66, s66, 0
	s_cmp_gt_u32 s67, 29
	s_cbranch_scc0 .LBB0_945
	s_barrier
	s_branch .Lp6_loop_exit
.LBB0_945:
	s_barrier
	s_add_u32 s40, s38, 0xfff80080
	s_addc_u32 s41, s39, -1
	s_cmp_eq_u32 s67, 28
	s_cselect_b32 s43, s29, s41
	s_cselect_b32 s42, s63, s40
	s_cselect_b32 s41, s27, s66
	s_cselect_b32 s40, s64, s65
	s_add_i32 m0, s37, 0xc000
	s_nop 0
	global_load_lds_dwordx4 v150, s[38:39]
	s_add_i32 m0, s37, 0xe000
	s_nop 0
	global_load_lds_dwordx4 v152, s[38:39]
	s_waitcnt vmcnt(10)
	s_barrier
	s_waitcnt lgkmcnt(0)
	v_mfma_f32_16x16x32_bf16 v[126:129], v[130:133], v[172:175], v[126:129]
	ds_read_b128 v[204:207], v171
	v_mfma_f32_16x16x32_bf16 v[122:125], v[138:141], v[172:175], v[122:125]
	v_mfma_f32_16x16x32_bf16 v[114:117], v[130:133], v[180:183], v[114:117]
	v_mfma_f32_16x16x32_bf16 v[106:109], v[138:141], v[180:183], v[106:109]
	v_mfma_f32_16x16x32_bf16 v[98:101], v[130:133], v[188:191], v[98:101]
	ds_read_b128 v[208:211], v171 offset:1024
	v_mfma_f32_16x16x32_bf16 v[90:93], v[138:141], v[188:191], v[90:93]
	v_mfma_f32_16x16x32_bf16 v[82:85], v[130:133], v[196:199], v[82:85]
	v_mfma_f32_16x16x32_bf16 v[74:77], v[138:141], v[196:199], v[74:77]
	v_mfma_f32_16x16x32_bf16 v[126:129], v[134:137], v[176:179], v[126:129]
	ds_read_b128 v[212:215], v171 offset:2048
	v_mfma_f32_16x16x32_bf16 v[122:125], v[142:145], v[176:179], v[122:125]
	v_mfma_f32_16x16x32_bf16 v[114:117], v[134:137], v[184:187], v[114:117]
	v_mfma_f32_16x16x32_bf16 v[106:109], v[142:145], v[184:187], v[106:109]
	v_mfma_f32_16x16x32_bf16 v[98:101], v[134:137], v[192:195], v[98:101]
	ds_read_b128 v[216:219], v171 offset:3072
	v_mfma_f32_16x16x32_bf16 v[90:93], v[142:145], v[192:195], v[90:93]
	v_mfma_f32_16x16x32_bf16 v[82:85], v[134:137], v[200:203], v[82:85]
	v_mfma_f32_16x16x32_bf16 v[74:77], v[142:145], v[200:203], v[74:77]
	s_barrier
	s_add_i32 s68, s59, s47
	s_add_u32 s96, s40, 0x80
	s_addc_u32 s97, s41, 0
	s_mov_b32 m0, s68
	s_nop 0
	global_load_lds_dwordx4 v146, s[40:41]
	s_add_i32 m0, s68, 0x2000
	s_nop 0
	global_load_lds_dwordx4 v148, s[40:41]
	s_waitcnt vmcnt(10)
	s_barrier
	s_waitcnt lgkmcnt(0)
	v_mfma_f32_16x16x32_bf16 v[118:121], v[204:207], v[172:175], v[118:121]
	ds_read_b128 v[224:227], v170 offset:16384
	v_mfma_f32_16x16x32_bf16 v[110:113], v[212:215], v[172:175], v[110:113]
	v_mfma_f32_16x16x32_bf16 v[102:105], v[204:207], v[180:183], v[102:105]
	ds_read_b128 v[228:231], v170 offset:17408
	v_mfma_f32_16x16x32_bf16 v[94:97], v[212:215], v[180:183], v[94:97]
	v_mfma_f32_16x16x32_bf16 v[86:89], v[204:207], v[188:191], v[86:89]
	ds_read_b128 v[232:235], v170 offset:18432
	v_mfma_f32_16x16x32_bf16 v[78:81], v[212:215], v[188:191], v[78:81]
	v_mfma_f32_16x16x32_bf16 v[70:73], v[204:207], v[196:199], v[70:73]
	ds_read_b128 v[236:239], v170 offset:19456
	v_mfma_f32_16x16x32_bf16 v[66:69], v[212:215], v[196:199], v[66:69]
	v_mfma_f32_16x16x32_bf16 v[118:121], v[208:211], v[176:179], v[118:121]
	ds_read_b128 v[240:243], v170 offset:20480
	v_mfma_f32_16x16x32_bf16 v[110:113], v[216:219], v[176:179], v[110:113]
	v_mfma_f32_16x16x32_bf16 v[102:105], v[208:211], v[184:187], v[102:105]
	ds_read_b128 v[244:247], v170 offset:21504
	v_mfma_f32_16x16x32_bf16 v[94:97], v[216:219], v[184:187], v[94:97]
	v_mfma_f32_16x16x32_bf16 v[86:89], v[208:211], v[192:195], v[86:89]
	ds_read_b128 v[248:251], v170 offset:22528
	v_mfma_f32_16x16x32_bf16 v[78:81], v[216:219], v[192:195], v[78:81]
	v_mfma_f32_16x16x32_bf16 v[70:73], v[208:211], v[200:203], v[70:73]
	ds_read_b128 v[220:223], v170 offset:23552
	v_mfma_f32_16x16x32_bf16 v[66:69], v[216:219], v[200:203], v[66:69]
	s_barrier
	s_mov_b32 m0, s37
	s_add_u32 s94, s42, 0x80
	s_addc_u32 s95, s43, 0
	global_load_lds_dwordx4 v146, s[42:43]
	s_mov_b32 m0, s50
	s_nop 0
	global_load_lds_dwordx4 v148, s[42:43]
	s_waitcnt vmcnt(8)
	s_barrier
	s_waitcnt lgkmcnt(0)
	v_mfma_f32_16x16x32_bf16 v[62:65], v[130:133], v[224:227], v[62:65]
	ds_read_b128 v[172:175], v170 offset:32768
	v_mfma_f32_16x16x32_bf16 v[58:61], v[138:141], v[224:227], v[58:61]
	v_mfma_f32_16x16x32_bf16 v[54:57], v[130:133], v[232:235], v[54:57]
	ds_read_b128 v[176:179], v170 offset:33792
	v_mfma_f32_16x16x32_bf16 v[46:49], v[138:141], v[232:235], v[46:49]
	v_mfma_f32_16x16x32_bf16 v[38:41], v[130:133], v[240:243], v[38:41]
	ds_read_b128 v[180:183], v170 offset:34816
	v_mfma_f32_16x16x32_bf16 v[30:33], v[138:141], v[240:243], v[30:33]
	v_mfma_f32_16x16x32_bf16 v[22:25], v[130:133], v[248:251], v[22:25]
	ds_read_b128 v[184:187], v170 offset:35840
	v_mfma_f32_16x16x32_bf16 v[14:17], v[138:141], v[248:251], v[14:17]
	v_mfma_f32_16x16x32_bf16 v[62:65], v[134:137], v[228:231], v[62:65]
	ds_read_b128 v[188:191], v170 offset:36864
	v_mfma_f32_16x16x32_bf16 v[58:61], v[142:145], v[228:231], v[58:61]
	v_mfma_f32_16x16x32_bf16 v[54:57], v[134:137], v[236:239], v[54:57]
	ds_read_b128 v[192:195], v170 offset:37888
	v_mfma_f32_16x16x32_bf16 v[46:49], v[142:145], v[236:239], v[46:49]
	v_mfma_f32_16x16x32_bf16 v[38:41], v[134:137], v[244:247], v[38:41]
	ds_read_b128 v[196:199], v170 offset:38912
	v_mfma_f32_16x16x32_bf16 v[30:33], v[142:145], v[244:247], v[30:33]
	v_mfma_f32_16x16x32_bf16 v[22:25], v[134:137], v[220:223], v[22:25]
	ds_read_b128 v[200:203], v170 offset:39936
	v_mfma_f32_16x16x32_bf16 v[14:17], v[142:145], v[220:223], v[14:17]
	s_barrier
	s_add_u32 s68, s40, 0x80000
	s_addc_u32 s69, s41, 0
	s_add_i32 s70, s60, s47
	s_mov_b32 m0, s70
	s_nop 0
	global_load_lds_dwordx4 v146, s[68:69]
	s_add_i32 m0, s70, 0x2000
	s_nop 0
	global_load_lds_dwordx4 v148, s[68:69]
	s_waitcnt vmcnt(10)
	s_barrier
	s_waitcnt lgkmcnt(0)
	v_mfma_f32_16x16x32_bf16 v[50:53], v[204:207], v[224:227], v[50:53]
	ds_read_b128 v[130:133], v158
	v_mfma_f32_16x16x32_bf16 v[42:45], v[212:215], v[224:227], v[42:45]
	v_mfma_f32_16x16x32_bf16 v[34:37], v[204:207], v[232:235], v[34:37]
	v_mfma_f32_16x16x32_bf16 v[26:29], v[212:215], v[232:235], v[26:29]
	v_mfma_f32_16x16x32_bf16 v[18:21], v[204:207], v[240:243], v[18:21]
	ds_read_b128 v[134:137], v158 offset:1024
	v_mfma_f32_16x16x32_bf16 v[10:13], v[212:215], v[240:243], v[10:13]
	v_mfma_f32_16x16x32_bf16 v[6:9], v[204:207], v[248:251], v[6:9]
	v_mfma_f32_16x16x32_bf16 v[2:5], v[212:215], v[248:251], v[2:5]
	v_mfma_f32_16x16x32_bf16 v[50:53], v[208:211], v[228:231], v[50:53]
	ds_read_b128 v[138:141], v158 offset:2048
	v_mfma_f32_16x16x32_bf16 v[42:45], v[216:219], v[228:231], v[42:45]
	v_mfma_f32_16x16x32_bf16 v[34:37], v[208:211], v[236:239], v[34:37]
	v_mfma_f32_16x16x32_bf16 v[26:29], v[216:219], v[236:239], v[26:29]
	v_mfma_f32_16x16x32_bf16 v[18:21], v[208:211], v[244:247], v[18:21]
	ds_read_b128 v[142:145], v158 offset:3072
	v_mfma_f32_16x16x32_bf16 v[10:13], v[216:219], v[244:247], v[10:13]
	v_mfma_f32_16x16x32_bf16 v[6:9], v[208:211], v[220:223], v[6:9]
	v_mfma_f32_16x16x32_bf16 v[2:5], v[216:219], v[220:223], v[2:5]
	s_barrier
	s_add_i32 s70, 0, 0x18000
	s_add_u32 s42, s42, 0x80000
	s_addc_u32 s43, s43, 0
	s_mov_b32 m0, s51
	s_nop 0
	global_load_lds_dwordx4 v146, s[42:43]
	s_mov_b32 m0, s52
	s_nop 0
	global_load_lds_dwordx4 v148, s[42:43]
	s_waitcnt vmcnt(10)
	s_barrier
	s_waitcnt lgkmcnt(0)
	v_mfma_f32_16x16x32_bf16 v[126:129], v[130:133], v[172:175], v[126:129]
	ds_read_b128 v[204:207], v159
	v_mfma_f32_16x16x32_bf16 v[122:125], v[138:141], v[172:175], v[122:125]
	v_mfma_f32_16x16x32_bf16 v[114:117], v[130:133], v[180:183], v[114:117]
	v_mfma_f32_16x16x32_bf16 v[106:109], v[138:141], v[180:183], v[106:109]
	v_mfma_f32_16x16x32_bf16 v[98:101], v[130:133], v[188:191], v[98:101]
	ds_read_b128 v[208:211], v159 offset:1024
	v_mfma_f32_16x16x32_bf16 v[90:93], v[138:141], v[188:191], v[90:93]
	v_mfma_f32_16x16x32_bf16 v[82:85], v[130:133], v[196:199], v[82:85]
	v_mfma_f32_16x16x32_bf16 v[74:77], v[138:141], v[196:199], v[74:77]
	v_mfma_f32_16x16x32_bf16 v[126:129], v[134:137], v[176:179], v[126:129]
	ds_read_b128 v[212:215], v159 offset:2048
	v_mfma_f32_16x16x32_bf16 v[122:125], v[142:145], v[176:179], v[122:125]
	v_mfma_f32_16x16x32_bf16 v[114:117], v[134:137], v[184:187], v[114:117]
	v_mfma_f32_16x16x32_bf16 v[106:109], v[142:145], v[184:187], v[106:109]
	v_mfma_f32_16x16x32_bf16 v[98:101], v[134:137], v[192:195], v[98:101]
	ds_read_b128 v[216:219], v159 offset:3072
	v_mfma_f32_16x16x32_bf16 v[90:93], v[142:145], v[192:195], v[90:93]
	v_mfma_f32_16x16x32_bf16 v[82:85], v[134:137], v[200:203], v[82:85]
	v_mfma_f32_16x16x32_bf16 v[74:77], v[142:145], v[200:203], v[74:77]
	s_barrier
	s_add_i32 s84, 0, 0x1c000
	s_add_i32 s85, s70, s47
	s_mov_b32 m0, s85
	s_nop 0
	global_load_lds_dwordx4 v146, s[96:97]
	s_add_i32 m0, s85, 0x2000
	s_nop 0
	global_load_lds_dwordx4 v148, s[96:97]
	s_waitcnt vmcnt(10)
	s_barrier
	s_waitcnt lgkmcnt(0)
	v_mfma_f32_16x16x32_bf16 v[118:121], v[204:207], v[172:175], v[118:121]
	ds_read_b128 v[224:227], v170 offset:49152
	v_mfma_f32_16x16x32_bf16 v[110:113], v[212:215], v[172:175], v[110:113]
	v_mfma_f32_16x16x32_bf16 v[102:105], v[204:207], v[180:183], v[102:105]
	ds_read_b128 v[228:231], v170 offset:50176
	v_mfma_f32_16x16x32_bf16 v[94:97], v[212:215], v[180:183], v[94:97]
	v_mfma_f32_16x16x32_bf16 v[86:89], v[204:207], v[188:191], v[86:89]
	ds_read_b128 v[232:235], v170 offset:51200
	v_mfma_f32_16x16x32_bf16 v[78:81], v[212:215], v[188:191], v[78:81]
	v_mfma_f32_16x16x32_bf16 v[70:73], v[204:207], v[196:199], v[70:73]
	ds_read_b128 v[236:239], v170 offset:52224
	v_mfma_f32_16x16x32_bf16 v[66:69], v[212:215], v[196:199], v[66:69]
	v_mfma_f32_16x16x32_bf16 v[118:121], v[208:211], v[176:179], v[118:121]
	ds_read_b128 v[240:243], v170 offset:53248
	v_mfma_f32_16x16x32_bf16 v[110:113], v[216:219], v[176:179], v[110:113]
	v_mfma_f32_16x16x32_bf16 v[102:105], v[208:211], v[184:187], v[102:105]
	ds_read_b128 v[244:247], v170 offset:54272
	v_mfma_f32_16x16x32_bf16 v[94:97], v[216:219], v[184:187], v[94:97]
	v_mfma_f32_16x16x32_bf16 v[86:89], v[208:211], v[192:195], v[86:89]
	ds_read_b128 v[248:251], v170 offset:55296
	v_mfma_f32_16x16x32_bf16 v[78:81], v[216:219], v[192:195], v[78:81]
	v_mfma_f32_16x16x32_bf16 v[70:73], v[208:211], v[200:203], v[70:73]
	ds_read_b128 v[220:223], v170 offset:56320
	v_mfma_f32_16x16x32_bf16 v[66:69], v[216:219], v[200:203], v[66:69]
	s_barrier
	s_mov_b32 m0, s57
	s_nop 0
	global_load_lds_dwordx4 v146, s[94:95]
	s_mov_b32 m0, s58
	s_nop 0
	global_load_lds_dwordx4 v148, s[94:95]
	s_waitcnt vmcnt(8)
	s_barrier
	s_waitcnt lgkmcnt(0)
	v_mfma_f32_16x16x32_bf16 v[62:65], v[130:133], v[224:227], v[62:65]
	ds_read_b128 v[172:175], v170
	v_mfma_f32_16x16x32_bf16 v[58:61], v[138:141], v[224:227], v[58:61]
	v_mfma_f32_16x16x32_bf16 v[54:57], v[130:133], v[232:235], v[54:57]
	ds_read_b128 v[176:179], v170 offset:1024
	v_mfma_f32_16x16x32_bf16 v[46:49], v[138:141], v[232:235], v[46:49]
	v_mfma_f32_16x16x32_bf16 v[38:41], v[130:133], v[240:243], v[38:41]
	ds_read_b128 v[180:183], v170 offset:2048
	v_mfma_f32_16x16x32_bf16 v[30:33], v[138:141], v[240:243], v[30:33]
	v_mfma_f32_16x16x32_bf16 v[22:25], v[130:133], v[248:251], v[22:25]
	ds_read_b128 v[184:187], v170 offset:3072
	v_mfma_f32_16x16x32_bf16 v[14:17], v[138:141], v[248:251], v[14:17]
	v_mfma_f32_16x16x32_bf16 v[62:65], v[134:137], v[228:231], v[62:65]
	ds_read_b128 v[188:191], v170 offset:4096
	v_mfma_f32_16x16x32_bf16 v[58:61], v[142:145], v[228:231], v[58:61]
	v_mfma_f32_16x16x32_bf16 v[54:57], v[134:137], v[236:239], v[54:57]
	ds_read_b128 v[192:195], v170 offset:5120
	v_mfma_f32_16x16x32_bf16 v[46:49], v[142:145], v[236:239], v[46:49]
	v_mfma_f32_16x16x32_bf16 v[38:41], v[134:137], v[244:247], v[38:41]
	ds_read_b128 v[196:199], v170 offset:6144
	v_mfma_f32_16x16x32_bf16 v[30:33], v[142:145], v[244:247], v[30:33]
	v_mfma_f32_16x16x32_bf16 v[22:25], v[134:137], v[220:223], v[22:25]
	ds_read_b128 v[200:203], v170 offset:7168
	v_mfma_f32_16x16x32_bf16 v[14:17], v[142:145], v[220:223], v[14:17]
	s_barrier
	s_add_u32 s40, s40, 0x80080
	s_addc_u32 s41, s41, 0
	s_add_i32 s84, s84, s47
	s_mov_b32 m0, s84
	s_nop 0
	global_load_lds_dwordx4 v146, s[40:41]
	s_add_i32 m0, s84, 0x2000
	s_nop 0
	global_load_lds_dwordx4 v148, s[40:41]
	s_waitcnt vmcnt(10)
	s_barrier
	s_waitcnt lgkmcnt(0)
	v_mfma_f32_16x16x32_bf16 v[50:53], v[204:207], v[224:227], v[50:53]
	ds_read_b128 v[130:133], v167
	v_mfma_f32_16x16x32_bf16 v[42:45], v[212:215], v[224:227], v[42:45]
	v_mfma_f32_16x16x32_bf16 v[34:37], v[204:207], v[232:235], v[34:37]
	v_mfma_f32_16x16x32_bf16 v[26:29], v[212:215], v[232:235], v[26:29]
	v_mfma_f32_16x16x32_bf16 v[18:21], v[204:207], v[240:243], v[18:21]
	ds_read_b128 v[134:137], v167 offset:1024
	v_mfma_f32_16x16x32_bf16 v[10:13], v[212:215], v[240:243], v[10:13]
	v_mfma_f32_16x16x32_bf16 v[6:9], v[204:207], v[248:251], v[6:9]
	v_mfma_f32_16x16x32_bf16 v[2:5], v[212:215], v[248:251], v[2:5]
	v_mfma_f32_16x16x32_bf16 v[50:53], v[208:211], v[228:231], v[50:53]
	ds_read_b128 v[138:141], v167 offset:2048
	v_mfma_f32_16x16x32_bf16 v[42:45], v[216:219], v[228:231], v[42:45]
	v_mfma_f32_16x16x32_bf16 v[34:37], v[208:211], v[236:239], v[34:37]
	v_mfma_f32_16x16x32_bf16 v[26:29], v[216:219], v[236:239], v[26:29]
	v_mfma_f32_16x16x32_bf16 v[18:21], v[208:211], v[244:247], v[18:21]
	ds_read_b128 v[142:145], v167 offset:3072
	v_mfma_f32_16x16x32_bf16 v[10:13], v[216:219], v[244:247], v[10:13]
	v_mfma_f32_16x16x32_bf16 v[6:9], v[208:211], v[220:223], v[6:9]
	v_mfma_f32_16x16x32_bf16 v[2:5], v[216:219], v[220:223], v[2:5]
	s_add_i32 s67, s67, 2
	s_add_u32 s38, s38, 0x100
	s_addc_u32 s39, s39, 0
	s_add_u32 s65, s65, 0x100
	s_addc_u32 s66, s66, 0
	s_cmp_gt_u32 s67, 29
	s_cbranch_scc0 .LBB0_945
	s_barrier

.Lp8_nostage:
	s_add_u32 s50, s48, 0xfff80080
	s_addc_u32 s51, s49, -1
	s_cmp_eq_u32 s80, s87
	s_cselect_b32 s53, s41, s51
	s_cselect_b32 s52, s47, s50
	s_cselect_b32 s51, s39, s75
	s_cselect_b32 s50, s73, s74
	s_add_i32 m0, s21, 0xc000
	s_nop 0
	global_load_lds_dwordx4 v166, s[48:49]
	s_add_i32 m0, s21, 0xe000
	s_nop 0
	global_load_lds_dwordx4 v170, s[48:49]
	s_waitcnt vmcnt(10)
	s_barrier
	s_waitcnt lgkmcnt(0)
	v_mfma_f32_16x16x32_bf16 v[126:129], v[130:133], v[146:149], 0
	ds_read_b128 v[192:195], v242
	v_mfma_f32_16x16x32_bf16 v[122:125], v[138:141], v[146:149], 0
	v_mfma_f32_16x16x32_bf16 v[118:121], v[130:133], v[154:157], 0
	v_mfma_f32_16x16x32_bf16 v[114:117], v[138:141], v[154:157], 0
	v_mfma_f32_16x16x32_bf16 v[106:109], v[130:133], v[176:179], 0
	ds_read_b128 v[196:199], v242 offset:1024
	v_mfma_f32_16x16x32_bf16 v[98:101], v[138:141], v[176:179], 0
	v_mfma_f32_16x16x32_bf16 v[90:93], v[130:133], v[184:187], 0
	v_mfma_f32_16x16x32_bf16 v[82:85], v[138:141], v[184:187], 0
	v_mfma_f32_16x16x32_bf16 v[126:129], v[134:137], v[150:153], v[126:129]
	ds_read_b128 v[200:203], v242 offset:2048
	v_mfma_f32_16x16x32_bf16 v[122:125], v[142:145], v[150:153], v[122:125]
	v_mfma_f32_16x16x32_bf16 v[118:121], v[134:137], v[158:161], v[118:121]
	v_mfma_f32_16x16x32_bf16 v[114:117], v[142:145], v[158:161], v[114:117]
	v_mfma_f32_16x16x32_bf16 v[106:109], v[134:137], v[180:183], v[106:109]
	ds_read_b128 v[204:207], v242 offset:3072
	v_mfma_f32_16x16x32_bf16 v[98:101], v[142:145], v[180:183], v[98:101]
	v_mfma_f32_16x16x32_bf16 v[90:93], v[134:137], v[188:191], v[90:93]
	v_mfma_f32_16x16x32_bf16 v[82:85], v[142:145], v[188:191], v[82:85]
	s_barrier
	s_add_i32 s81, s68, s56
	s_add_u32 s96, s50, 0x80
	s_addc_u32 s97, s51, 0
	s_mov_b32 m0, s81
	s_nop 0
	global_load_lds_dwordx4 v162, s[50:51]
	s_add_i32 m0, s81, 0x2000
	s_nop 0
	global_load_lds_dwordx4 v164, s[50:51]
	s_waitcnt vmcnt(10)
	s_barrier
	s_waitcnt lgkmcnt(0)
	v_mfma_f32_16x16x32_bf16 v[110:113], v[192:195], v[146:149], 0
	ds_read_b128 v[208:211], v241 offset:16384
	v_mfma_f32_16x16x32_bf16 v[102:105], v[200:203], v[146:149], 0
	v_mfma_f32_16x16x32_bf16 v[94:97], v[192:195], v[154:157], 0
	ds_read_b128 v[212:215], v241 offset:17408
	v_mfma_f32_16x16x32_bf16 v[86:89], v[200:203], v[154:157], 0
	v_mfma_f32_16x16x32_bf16 v[78:81], v[192:195], v[176:179], 0
	ds_read_b128 v[216:219], v241 offset:18432
	v_mfma_f32_16x16x32_bf16 v[74:77], v[200:203], v[176:179], 0
	v_mfma_f32_16x16x32_bf16 v[70:73], v[192:195], v[184:187], 0
	ds_read_b128 v[220:223], v241 offset:19456
	v_mfma_f32_16x16x32_bf16 v[66:69], v[200:203], v[184:187], 0
	v_mfma_f32_16x16x32_bf16 v[110:113], v[196:199], v[150:153], v[110:113]
	ds_read_b128 v[224:227], v241 offset:20480
	v_mfma_f32_16x16x32_bf16 v[102:105], v[204:207], v[150:153], v[102:105]
	v_mfma_f32_16x16x32_bf16 v[94:97], v[196:199], v[158:161], v[94:97]
	ds_read_b128 v[228:231], v241 offset:21504
	v_mfma_f32_16x16x32_bf16 v[86:89], v[204:207], v[158:161], v[86:89]
	v_mfma_f32_16x16x32_bf16 v[78:81], v[196:199], v[180:183], v[78:81]
	ds_read_b128 v[232:235], v241 offset:22528
	v_mfma_f32_16x16x32_bf16 v[74:77], v[204:207], v[180:183], v[74:77]
	v_mfma_f32_16x16x32_bf16 v[70:73], v[196:199], v[188:191], v[70:73]
	ds_read_b128 v[246:249], v241 offset:23552
	v_mfma_f32_16x16x32_bf16 v[66:69], v[204:207], v[188:191], v[66:69]
	s_barrier
	s_mov_b32 m0, s21
	s_add_u32 s94, s52, 0x80
	s_addc_u32 s95, s53, 0
	global_load_lds_dwordx4 v162, s[52:53]
	s_mov_b32 m0, s59
	s_nop 0
	global_load_lds_dwordx4 v164, s[52:53]
	s_waitcnt vmcnt(8)
	s_barrier
	s_waitcnt lgkmcnt(0)
	v_mfma_f32_16x16x32_bf16 v[62:65], v[130:133], v[208:211], 0
	ds_read_b128 v[146:149], v241 offset:32768
	v_mfma_f32_16x16x32_bf16 v[58:61], v[138:141], v[208:211], 0
	v_mfma_f32_16x16x32_bf16 v[54:57], v[130:133], v[216:219], 0
	ds_read_b128 v[150:153], v241 offset:33792
	v_mfma_f32_16x16x32_bf16 v[50:53], v[138:141], v[216:219], 0
	v_mfma_f32_16x16x32_bf16 v[42:45], v[130:133], v[224:227], 0
	ds_read_b128 v[154:157], v241 offset:34816
	v_mfma_f32_16x16x32_bf16 v[34:37], v[138:141], v[224:227], 0
	v_mfma_f32_16x16x32_bf16 v[26:29], v[130:133], v[232:235], 0
	ds_read_b128 v[158:161], v241 offset:35840
	v_mfma_f32_16x16x32_bf16 v[18:21], v[138:141], v[232:235], 0
	v_mfma_f32_16x16x32_bf16 v[62:65], v[134:137], v[212:215], v[62:65]
	ds_read_b128 v[176:179], v241 offset:36864
	v_mfma_f32_16x16x32_bf16 v[58:61], v[142:145], v[212:215], v[58:61]
	v_mfma_f32_16x16x32_bf16 v[54:57], v[134:137], v[220:223], v[54:57]
	ds_read_b128 v[180:183], v241 offset:37888
	v_mfma_f32_16x16x32_bf16 v[50:53], v[142:145], v[220:223], v[50:53]
	v_mfma_f32_16x16x32_bf16 v[42:45], v[134:137], v[228:231], v[42:45]
	ds_read_b128 v[184:187], v241 offset:38912
	v_mfma_f32_16x16x32_bf16 v[34:37], v[142:145], v[228:231], v[34:37]
	v_mfma_f32_16x16x32_bf16 v[26:29], v[134:137], v[246:249], v[26:29]
	ds_read_b128 v[188:191], v241 offset:39936
	v_mfma_f32_16x16x32_bf16 v[18:21], v[142:145], v[246:249], v[18:21]
	s_barrier
	s_add_u32 s82, s50, 0x80000
	s_addc_u32 s83, s51, 0
	s_add_i32 s81, s69, s56
	s_mov_b32 m0, s81
	s_nop 0
	global_load_lds_dwordx4 v162, s[82:83]
	s_add_i32 m0, s81, 0x2000
	s_nop 0
	global_load_lds_dwordx4 v164, s[82:83]
	s_waitcnt vmcnt(10)
	s_barrier
	s_waitcnt lgkmcnt(0)
	v_mfma_f32_16x16x32_bf16 v[46:49], v[192:195], v[208:211], 0
	ds_read_b128 v[130:133], v168
	v_mfma_f32_16x16x32_bf16 v[38:41], v[200:203], v[208:211], 0
	v_mfma_f32_16x16x32_bf16 v[30:33], v[192:195], v[216:219], 0
	v_mfma_f32_16x16x32_bf16 v[22:25], v[200:203], v[216:219], 0
	v_mfma_f32_16x16x32_bf16 v[14:17], v[192:195], v[224:227], 0
	ds_read_b128 v[134:137], v168 offset:1024
	v_mfma_f32_16x16x32_bf16 v[10:13], v[200:203], v[224:227], 0
	v_mfma_f32_16x16x32_bf16 v[6:9], v[192:195], v[232:235], 0
	v_mfma_f32_16x16x32_bf16 v[2:5], v[200:203], v[232:235], 0
	v_mfma_f32_16x16x32_bf16 v[46:49], v[196:199], v[212:215], v[46:49]
	ds_read_b128 v[138:141], v168 offset:2048
	v_mfma_f32_16x16x32_bf16 v[38:41], v[204:207], v[212:215], v[38:41]
	v_mfma_f32_16x16x32_bf16 v[30:33], v[196:199], v[220:223], v[30:33]
	v_mfma_f32_16x16x32_bf16 v[22:25], v[204:207], v[220:223], v[22:25]
	v_mfma_f32_16x16x32_bf16 v[14:17], v[196:199], v[228:231], v[14:17]
	ds_read_b128 v[142:145], v168 offset:3072
	v_mfma_f32_16x16x32_bf16 v[10:13], v[204:207], v[228:231], v[10:13]
	v_mfma_f32_16x16x32_bf16 v[6:9], v[196:199], v[246:249], v[6:9]
	v_mfma_f32_16x16x32_bf16 v[2:5], v[204:207], v[246:249], v[2:5]
	s_barrier
	s_add_i32 s81, 0, 0x18000
	s_add_u32 s52, s52, 0x80000
	s_addc_u32 s53, s53, 0
	s_mov_b32 m0, s60
	s_nop 0
	global_load_lds_dwordx4 v162, s[52:53]
	s_mov_b32 m0, s61
	s_nop 0
	global_load_lds_dwordx4 v164, s[52:53]
	s_waitcnt vmcnt(10)
	s_barrier
	s_waitcnt lgkmcnt(0)
	v_mfma_f32_16x16x32_bf16 v[126:129], v[130:133], v[146:149], v[126:129]
	ds_read_b128 v[192:195], v169
	v_mfma_f32_16x16x32_bf16 v[122:125], v[138:141], v[146:149], v[122:125]
	v_mfma_f32_16x16x32_bf16 v[118:121], v[130:133], v[154:157], v[118:121]
	v_mfma_f32_16x16x32_bf16 v[114:117], v[138:141], v[154:157], v[114:117]
	v_mfma_f32_16x16x32_bf16 v[106:109], v[130:133], v[176:179], v[106:109]
	ds_read_b128 v[196:199], v169 offset:1024
	v_mfma_f32_16x16x32_bf16 v[98:101], v[138:141], v[176:179], v[98:101]
	v_mfma_f32_16x16x32_bf16 v[90:93], v[130:133], v[184:187], v[90:93]
	v_mfma_f32_16x16x32_bf16 v[82:85], v[138:141], v[184:187], v[82:85]
	v_mfma_f32_16x16x32_bf16 v[126:129], v[134:137], v[150:153], v[126:129]
	ds_read_b128 v[200:203], v169 offset:2048
	v_mfma_f32_16x16x32_bf16 v[122:125], v[142:145], v[150:153], v[122:125]
	v_mfma_f32_16x16x32_bf16 v[118:121], v[134:137], v[158:161], v[118:121]
	v_mfma_f32_16x16x32_bf16 v[114:117], v[142:145], v[158:161], v[114:117]
	v_mfma_f32_16x16x32_bf16 v[106:109], v[134:137], v[180:183], v[106:109]
	ds_read_b128 v[204:207], v169 offset:3072
	v_mfma_f32_16x16x32_bf16 v[98:101], v[142:145], v[180:183], v[98:101]
	v_mfma_f32_16x16x32_bf16 v[90:93], v[134:137], v[188:191], v[90:93]
	v_mfma_f32_16x16x32_bf16 v[82:85], v[142:145], v[188:191], v[82:85]
	s_barrier
	s_add_i32 s52, 0, 0x1c000
	s_add_i32 s53, s81, s56
	s_mov_b32 m0, s53
	s_nop 0
	global_load_lds_dwordx4 v162, s[96:97]
	s_add_i32 m0, s53, 0x2000
	s_nop 0
	global_load_lds_dwordx4 v164, s[96:97]
	s_waitcnt vmcnt(10)
	s_barrier
	s_waitcnt lgkmcnt(0)
	v_mfma_f32_16x16x32_bf16 v[110:113], v[192:195], v[146:149], v[110:113]
	ds_read_b128 v[208:211], v241 offset:49152
	v_mfma_f32_16x16x32_bf16 v[102:105], v[200:203], v[146:149], v[102:105]
	v_mfma_f32_16x16x32_bf16 v[94:97], v[192:195], v[154:157], v[94:97]
	ds_read_b128 v[212:215], v241 offset:50176
	v_mfma_f32_16x16x32_bf16 v[86:89], v[200:203], v[154:157], v[86:89]
	v_mfma_f32_16x16x32_bf16 v[78:81], v[192:195], v[176:179], v[78:81]
	ds_read_b128 v[216:219], v241 offset:51200
	v_mfma_f32_16x16x32_bf16 v[74:77], v[200:203], v[176:179], v[74:77]
	v_mfma_f32_16x16x32_bf16 v[70:73], v[192:195], v[184:187], v[70:73]
	ds_read_b128 v[220:223], v241 offset:52224
	v_mfma_f32_16x16x32_bf16 v[66:69], v[200:203], v[184:187], v[66:69]
	v_mfma_f32_16x16x32_bf16 v[110:113], v[196:199], v[150:153], v[110:113]
	ds_read_b128 v[224:227], v241 offset:53248
	v_mfma_f32_16x16x32_bf16 v[102:105], v[204:207], v[150:153], v[102:105]
	v_mfma_f32_16x16x32_bf16 v[94:97], v[196:199], v[158:161], v[94:97]
	ds_read_b128 v[228:231], v241 offset:54272
	v_mfma_f32_16x16x32_bf16 v[86:89], v[204:207], v[158:161], v[86:89]
	v_mfma_f32_16x16x32_bf16 v[78:81], v[196:199], v[180:183], v[78:81]
	ds_read_b128 v[232:235], v241 offset:55296
	v_mfma_f32_16x16x32_bf16 v[74:77], v[204:207], v[180:183], v[74:77]
	v_mfma_f32_16x16x32_bf16 v[70:73], v[196:199], v[188:191], v[70:73]
	ds_read_b128 v[246:249], v241 offset:56320
	v_mfma_f32_16x16x32_bf16 v[66:69], v[204:207], v[188:191], v[66:69]
	s_barrier
	s_mov_b32 m0, s64
	s_nop 0
	global_load_lds_dwordx4 v162, s[94:95]
	s_mov_b32 m0, s65
	s_nop 0
	global_load_lds_dwordx4 v164, s[94:95]
	s_waitcnt vmcnt(8)
	s_barrier
	s_waitcnt lgkmcnt(0)
	v_mfma_f32_16x16x32_bf16 v[62:65], v[130:133], v[208:211], v[62:65]
	ds_read_b128 v[146:149], v241
	v_mfma_f32_16x16x32_bf16 v[58:61], v[138:141], v[208:211], v[58:61]
	v_mfma_f32_16x16x32_bf16 v[54:57], v[130:133], v[216:219], v[54:57]
	ds_read_b128 v[150:153], v241 offset:1024
	v_mfma_f32_16x16x32_bf16 v[50:53], v[138:141], v[216:219], v[50:53]
	v_mfma_f32_16x16x32_bf16 v[42:45], v[130:133], v[224:227], v[42:45]
	ds_read_b128 v[154:157], v241 offset:2048
	v_mfma_f32_16x16x32_bf16 v[34:37], v[138:141], v[224:227], v[34:37]
	v_mfma_f32_16x16x32_bf16 v[26:29], v[130:133], v[232:235], v[26:29]
	ds_read_b128 v[158:161], v241 offset:3072
	v_mfma_f32_16x16x32_bf16 v[18:21], v[138:141], v[232:235], v[18:21]
	v_mfma_f32_16x16x32_bf16 v[62:65], v[134:137], v[212:215], v[62:65]
	ds_read_b128 v[176:179], v241 offset:4096
	v_mfma_f32_16x16x32_bf16 v[58:61], v[142:145], v[212:215], v[58:61]
	v_mfma_f32_16x16x32_bf16 v[54:57], v[134:137], v[220:223], v[54:57]
	ds_read_b128 v[180:183], v241 offset:5120
	v_mfma_f32_16x16x32_bf16 v[50:53], v[142:145], v[220:223], v[50:53]
	v_mfma_f32_16x16x32_bf16 v[42:45], v[134:137], v[228:231], v[42:45]
	ds_read_b128 v[184:187], v241 offset:6144
	v_mfma_f32_16x16x32_bf16 v[34:37], v[142:145], v[228:231], v[34:37]
	v_mfma_f32_16x16x32_bf16 v[26:29], v[134:137], v[246:249], v[26:29]
	ds_read_b128 v[188:191], v241 offset:7168
	v_mfma_f32_16x16x32_bf16 v[18:21], v[142:145], v[246:249], v[18:21]
	s_barrier
	s_add_u32 s50, s50, 0x80080
	s_addc_u32 s51, s51, 0
	s_add_i32 s52, s52, s56
	s_mov_b32 m0, s52
	s_nop 0
	global_load_lds_dwordx4 v162, s[50:51]
	s_add_i32 m0, s52, 0x2000
	s_nop 0
	global_load_lds_dwordx4 v164, s[50:51]
	s_waitcnt vmcnt(10)
	s_barrier
	s_waitcnt lgkmcnt(0)
	v_mfma_f32_16x16x32_bf16 v[46:49], v[192:195], v[208:211], v[46:49]
	ds_read_b128 v[130:133], v240
	v_mfma_f32_16x16x32_bf16 v[38:41], v[200:203], v[208:211], v[38:41]
	v_mfma_f32_16x16x32_bf16 v[30:33], v[192:195], v[216:219], v[30:33]
	v_mfma_f32_16x16x32_bf16 v[22:25], v[200:203], v[216:219], v[22:25]
	v_mfma_f32_16x16x32_bf16 v[14:17], v[192:195], v[224:227], v[14:17]
	ds_read_b128 v[134:137], v240 offset:1024
	v_mfma_f32_16x16x32_bf16 v[10:13], v[200:203], v[224:227], v[10:13]
	v_mfma_f32_16x16x32_bf16 v[6:9], v[192:195], v[232:235], v[6:9]
	v_mfma_f32_16x16x32_bf16 v[2:5], v[200:203], v[232:235], v[2:5]
	v_mfma_f32_16x16x32_bf16 v[46:49], v[196:199], v[212:215], v[46:49]
	ds_read_b128 v[138:141], v240 offset:2048
	v_mfma_f32_16x16x32_bf16 v[38:41], v[204:207], v[212:215], v[38:41]
	v_mfma_f32_16x16x32_bf16 v[30:33], v[196:199], v[220:223], v[30:33]
	v_mfma_f32_16x16x32_bf16 v[22:25], v[204:207], v[220:223], v[22:25]
	v_mfma_f32_16x16x32_bf16 v[14:17], v[196:199], v[228:231], v[14:17]
	ds_read_b128 v[142:145], v240 offset:3072
	v_mfma_f32_16x16x32_bf16 v[10:13], v[204:207], v[228:231], v[10:13]
	v_mfma_f32_16x16x32_bf16 v[6:9], v[196:199], v[246:249], v[6:9]
	v_mfma_f32_16x16x32_bf16 v[2:5], v[204:207], v[246:249], v[2:5]
	s_add_i32 s80, s80, 2
	s_add_u32 s48, s48, 0x100
	s_addc_u32 s49, s49, 0
	s_add_u32 s74, s74, 0x100
	s_addc_u32 s75, s75, 0
	s_cmp_gt_u32 s80, s87
	s_cbranch_scc0 .LBB0_1098
	s_barrier
	s_branch .Lp8_loop_exit
.LBB0_1098:
	s_barrier
	s_add_u32 s50, s48, 0xfff80080
	s_addc_u32 s51, s49, -1
	s_cmp_eq_u32 s80, s87
	s_cselect_b32 s53, s41, s51
	s_cselect_b32 s52, s47, s50
	s_cselect_b32 s51, s39, s75
	s_cselect_b32 s50, s73, s74
	s_add_i32 m0, s21, 0xc000
	s_nop 0
	global_load_lds_dwordx4 v166, s[48:49]
	s_add_i32 m0, s21, 0xe000
	s_nop 0
	global_load_lds_dwordx4 v170, s[48:49]
	s_waitcnt vmcnt(10)
	s_barrier
	s_waitcnt lgkmcnt(0)
	v_mfma_f32_16x16x32_bf16 v[126:129], v[130:133], v[146:149], v[126:129]
	ds_read_b128 v[192:195], v242
	v_mfma_f32_16x16x32_bf16 v[122:125], v[138:141], v[146:149], v[122:125]
	v_mfma_f32_16x16x32_bf16 v[118:121], v[130:133], v[154:157], v[118:121]
	v_mfma_f32_16x16x32_bf16 v[114:117], v[138:141], v[154:157], v[114:117]
	v_mfma_f32_16x16x32_bf16 v[106:109], v[130:133], v[176:179], v[106:109]
	ds_read_b128 v[196:199], v242 offset:1024
	v_mfma_f32_16x16x32_bf16 v[98:101], v[138:141], v[176:179], v[98:101]
	v_mfma_f32_16x16x32_bf16 v[90:93], v[130:133], v[184:187], v[90:93]
	v_mfma_f32_16x16x32_bf16 v[82:85], v[138:141], v[184:187], v[82:85]
	v_mfma_f32_16x16x32_bf16 v[126:129], v[134:137], v[150:153], v[126:129]
	ds_read_b128 v[200:203], v242 offset:2048
	v_mfma_f32_16x16x32_bf16 v[122:125], v[142:145], v[150:153], v[122:125]
	v_mfma_f32_16x16x32_bf16 v[118:121], v[134:137], v[158:161], v[118:121]
	v_mfma_f32_16x16x32_bf16 v[114:117], v[142:145], v[158:161], v[114:117]
	v_mfma_f32_16x16x32_bf16 v[106:109], v[134:137], v[180:183], v[106:109]
	ds_read_b128 v[204:207], v242 offset:3072
	v_mfma_f32_16x16x32_bf16 v[98:101], v[142:145], v[180:183], v[98:101]
	v_mfma_f32_16x16x32_bf16 v[90:93], v[134:137], v[188:191], v[90:93]
	v_mfma_f32_16x16x32_bf16 v[82:85], v[142:145], v[188:191], v[82:85]
	s_barrier
	s_add_i32 s81, s68, s56
	s_add_u32 s96, s50, 0x80
	s_addc_u32 s97, s51, 0
	s_mov_b32 m0, s81
	s_nop 0
	global_load_lds_dwordx4 v162, s[50:51]
	s_add_i32 m0, s81, 0x2000
	s_nop 0
	global_load_lds_dwordx4 v164, s[50:51]
	s_waitcnt vmcnt(10)
	s_barrier
	s_waitcnt lgkmcnt(0)
	v_mfma_f32_16x16x32_bf16 v[110:113], v[192:195], v[146:149], v[110:113]
	ds_read_b128 v[208:211], v241 offset:16384
	v_mfma_f32_16x16x32_bf16 v[102:105], v[200:203], v[146:149], v[102:105]
	v_mfma_f32_16x16x32_bf16 v[94:97], v[192:195], v[154:157], v[94:97]
	ds_read_b128 v[212:215], v241 offset:17408
	v_mfma_f32_16x16x32_bf16 v[86:89], v[200:203], v[154:157], v[86:89]
	v_mfma_f32_16x16x32_bf16 v[78:81], v[192:195], v[176:179], v[78:81]
	ds_read_b128 v[216:219], v241 offset:18432
	v_mfma_f32_16x16x32_bf16 v[74:77], v[200:203], v[176:179], v[74:77]
	v_mfma_f32_16x16x32_bf16 v[70:73], v[192:195], v[184:187], v[70:73]
	ds_read_b128 v[220:223], v241 offset:19456
	v_mfma_f32_16x16x32_bf16 v[66:69], v[200:203], v[184:187], v[66:69]
	v_mfma_f32_16x16x32_bf16 v[110:113], v[196:199], v[150:153], v[110:113]
	ds_read_b128 v[224:227], v241 offset:20480
	v_mfma_f32_16x16x32_bf16 v[102:105], v[204:207], v[150:153], v[102:105]
	v_mfma_f32_16x16x32_bf16 v[94:97], v[196:199], v[158:161], v[94:97]
	ds_read_b128 v[228:231], v241 offset:21504
	v_mfma_f32_16x16x32_bf16 v[86:89], v[204:207], v[158:161], v[86:89]
	v_mfma_f32_16x16x32_bf16 v[78:81], v[196:199], v[180:183], v[78:81]
	ds_read_b128 v[232:235], v241 offset:22528
	v_mfma_f32_16x16x32_bf16 v[74:77], v[204:207], v[180:183], v[74:77]
	v_mfma_f32_16x16x32_bf16 v[70:73], v[196:199], v[188:191], v[70:73]
	ds_read_b128 v[246:249], v241 offset:23552
	v_mfma_f32_16x16x32_bf16 v[66:69], v[204:207], v[188:191], v[66:69]
	s_barrier
	s_mov_b32 m0, s21
	s_add_u32 s94, s52, 0x80
	s_addc_u32 s95, s53, 0
	global_load_lds_dwordx4 v162, s[52:53]
	s_mov_b32 m0, s59
	s_nop 0
	global_load_lds_dwordx4 v164, s[52:53]
	s_waitcnt vmcnt(8)
	s_barrier
	s_waitcnt lgkmcnt(0)
	v_mfma_f32_16x16x32_bf16 v[62:65], v[130:133], v[208:211], v[62:65]
	ds_read_b128 v[146:149], v241 offset:32768
	v_mfma_f32_16x16x32_bf16 v[58:61], v[138:141], v[208:211], v[58:61]
	v_mfma_f32_16x16x32_bf16 v[54:57], v[130:133], v[216:219], v[54:57]
	ds_read_b128 v[150:153], v241 offset:33792
	v_mfma_f32_16x16x32_bf16 v[50:53], v[138:141], v[216:219], v[50:53]
	v_mfma_f32_16x16x32_bf16 v[42:45], v[130:133], v[224:227], v[42:45]
	ds_read_b128 v[154:157], v241 offset:34816
	v_mfma_f32_16x16x32_bf16 v[34:37], v[138:141], v[224:227], v[34:37]
	v_mfma_f32_16x16x32_bf16 v[26:29], v[130:133], v[232:235], v[26:29]
	ds_read_b128 v[158:161], v241 offset:35840
	v_mfma_f32_16x16x32_bf16 v[18:21], v[138:141], v[232:235], v[18:21]
	v_mfma_f32_16x16x32_bf16 v[62:65], v[134:137], v[212:215], v[62:65]
	ds_read_b128 v[176:179], v241 offset:36864
	v_mfma_f32_16x16x32_bf16 v[58:61], v[142:145], v[212:215], v[58:61]
	v_mfma_f32_16x16x32_bf16 v[54:57], v[134:137], v[220:223], v[54:57]
	ds_read_b128 v[180:183], v241 offset:37888
	v_mfma_f32_16x16x32_bf16 v[50:53], v[142:145], v[220:223], v[50:53]
	v_mfma_f32_16x16x32_bf16 v[42:45], v[134:137], v[228:231], v[42:45]
	ds_read_b128 v[184:187], v241 offset:38912
	v_mfma_f32_16x16x32_bf16 v[34:37], v[142:145], v[228:231], v[34:37]
	v_mfma_f32_16x16x32_bf16 v[26:29], v[134:137], v[246:249], v[26:29]
	ds_read_b128 v[188:191], v241 offset:39936
	v_mfma_f32_16x16x32_bf16 v[18:21], v[142:145], v[246:249], v[18:21]
	s_barrier
	s_add_u32 s82, s50, 0x80000
	s_addc_u32 s83, s51, 0
	s_add_i32 s81, s69, s56
	s_mov_b32 m0, s81
	s_nop 0
	global_load_lds_dwordx4 v162, s[82:83]
	s_add_i32 m0, s81, 0x2000
	s_nop 0
	global_load_lds_dwordx4 v164, s[82:83]
	s_waitcnt vmcnt(10)
	s_barrier
	s_waitcnt lgkmcnt(0)
	v_mfma_f32_16x16x32_bf16 v[46:49], v[192:195], v[208:211], v[46:49]
	ds_read_b128 v[130:133], v168
	v_mfma_f32_16x16x32_bf16 v[38:41], v[200:203], v[208:211], v[38:41]
	v_mfma_f32_16x16x32_bf16 v[30:33], v[192:195], v[216:219], v[30:33]
	v_mfma_f32_16x16x32_bf16 v[22:25], v[200:203], v[216:219], v[22:25]
	v_mfma_f32_16x16x32_bf16 v[14:17], v[192:195], v[224:227], v[14:17]
	ds_read_b128 v[134:137], v168 offset:1024
	v_mfma_f32_16x16x32_bf16 v[10:13], v[200:203], v[224:227], v[10:13]
	v_mfma_f32_16x16x32_bf16 v[6:9], v[192:195], v[232:235], v[6:9]
	v_mfma_f32_16x16x32_bf16 v[2:5], v[200:203], v[232:235], v[2:5]
	v_mfma_f32_16x16x32_bf16 v[46:49], v[196:199], v[212:215], v[46:49]
	ds_read_b128 v[138:141], v168 offset:2048
	v_mfma_f32_16x16x32_bf16 v[38:41], v[204:207], v[212:215], v[38:41]
	v_mfma_f32_16x16x32_bf16 v[30:33], v[196:199], v[220:223], v[30:33]
	v_mfma_f32_16x16x32_bf16 v[22:25], v[204:207], v[220:223], v[22:25]
	v_mfma_f32_16x16x32_bf16 v[14:17], v[196:199], v[228:231], v[14:17]
	ds_read_b128 v[142:145], v168 offset:3072
	v_mfma_f32_16x16x32_bf16 v[10:13], v[204:207], v[228:231], v[10:13]
	v_mfma_f32_16x16x32_bf16 v[6:9], v[196:199], v[246:249], v[6:9]
	v_mfma_f32_16x16x32_bf16 v[2:5], v[204:207], v[246:249], v[2:5]
	s_barrier
	s_add_i32 s81, 0, 0x18000
	s_add_u32 s52, s52, 0x80000
	s_addc_u32 s53, s53, 0
	s_mov_b32 m0, s60
	s_nop 0
	global_load_lds_dwordx4 v162, s[52:53]
	s_mov_b32 m0, s61
	s_nop 0
	global_load_lds_dwordx4 v164, s[52:53]
	s_waitcnt vmcnt(10)
	s_barrier
	s_waitcnt lgkmcnt(0)
	v_mfma_f32_16x16x32_bf16 v[126:129], v[130:133], v[146:149], v[126:129]
	ds_read_b128 v[192:195], v169
	v_mfma_f32_16x16x32_bf16 v[122:125], v[138:141], v[146:149], v[122:125]
	v_mfma_f32_16x16x32_bf16 v[118:121], v[130:133], v[154:157], v[118:121]
	v_mfma_f32_16x16x32_bf16 v[114:117], v[138:141], v[154:157], v[114:117]
	v_mfma_f32_16x16x32_bf16 v[106:109], v[130:133], v[176:179], v[106:109]
	ds_read_b128 v[196:199], v169 offset:1024
	v_mfma_f32_16x16x32_bf16 v[98:101], v[138:141], v[176:179], v[98:101]
	v_mfma_f32_16x16x32_bf16 v[90:93], v[130:133], v[184:187], v[90:93]
	v_mfma_f32_16x16x32_bf16 v[82:85], v[138:141], v[184:187], v[82:85]
	v_mfma_f32_16x16x32_bf16 v[126:129], v[134:137], v[150:153], v[126:129]
	ds_read_b128 v[200:203], v169 offset:2048
	v_mfma_f32_16x16x32_bf16 v[122:125], v[142:145], v[150:153], v[122:125]
	v_mfma_f32_16x16x32_bf16 v[118:121], v[134:137], v[158:161], v[118:121]
	v_mfma_f32_16x16x32_bf16 v[114:117], v[142:145], v[158:161], v[114:117]
	v_mfma_f32_16x16x32_bf16 v[106:109], v[134:137], v[180:183], v[106:109]
	ds_read_b128 v[204:207], v169 offset:3072
	v_mfma_f32_16x16x32_bf16 v[98:101], v[142:145], v[180:183], v[98:101]
	v_mfma_f32_16x16x32_bf16 v[90:93], v[134:137], v[188:191], v[90:93]
	v_mfma_f32_16x16x32_bf16 v[82:85], v[142:145], v[188:191], v[82:85]
	s_barrier
	s_add_i32 s52, 0, 0x1c000
	s_add_i32 s53, s81, s56
	s_mov_b32 m0, s53
	s_nop 0
	global_load_lds_dwordx4 v162, s[96:97]
	s_add_i32 m0, s53, 0x2000
	s_nop 0
	global_load_lds_dwordx4 v164, s[96:97]
	s_waitcnt vmcnt(10)
	s_barrier
	s_waitcnt lgkmcnt(0)
	v_mfma_f32_16x16x32_bf16 v[110:113], v[192:195], v[146:149], v[110:113]
	ds_read_b128 v[208:211], v241 offset:49152
	v_mfma_f32_16x16x32_bf16 v[102:105], v[200:203], v[146:149], v[102:105]
	v_mfma_f32_16x16x32_bf16 v[94:97], v[192:195], v[154:157], v[94:97]
	ds_read_b128 v[212:215], v241 offset:50176
	v_mfma_f32_16x16x32_bf16 v[86:89], v[200:203], v[154:157], v[86:89]
	v_mfma_f32_16x16x32_bf16 v[78:81], v[192:195], v[176:179], v[78:81]
	ds_read_b128 v[216:219], v241 offset:51200
	v_mfma_f32_16x16x32_bf16 v[74:77], v[200:203], v[176:179], v[74:77]
	v_mfma_f32_16x16x32_bf16 v[70:73], v[192:195], v[184:187], v[70:73]
	ds_read_b128 v[220:223], v241 offset:52224
	v_mfma_f32_16x16x32_bf16 v[66:69], v[200:203], v[184:187], v[66:69]
	v_mfma_f32_16x16x32_bf16 v[110:113], v[196:199], v[150:153], v[110:113]
	ds_read_b128 v[224:227], v241 offset:53248
	v_mfma_f32_16x16x32_bf16 v[102:105], v[204:207], v[150:153], v[102:105]
	v_mfma_f32_16x16x32_bf16 v[94:97], v[196:199], v[158:161], v[94:97]
	ds_read_b128 v[228:231], v241 offset:54272
	v_mfma_f32_16x16x32_bf16 v[86:89], v[204:207], v[158:161], v[86:89]
	v_mfma_f32_16x16x32_bf16 v[78:81], v[196:199], v[180:183], v[78:81]
	ds_read_b128 v[232:235], v241 offset:55296
	v_mfma_f32_16x16x32_bf16 v[74:77], v[204:207], v[180:183], v[74:77]
	v_mfma_f32_16x16x32_bf16 v[70:73], v[196:199], v[188:191], v[70:73]
	ds_read_b128 v[246:249], v241 offset:56320
	v_mfma_f32_16x16x32_bf16 v[66:69], v[204:207], v[188:191], v[66:69]
	s_barrier
	s_mov_b32 m0, s64
	s_nop 0
	global_load_lds_dwordx4 v162, s[94:95]
	s_mov_b32 m0, s65
	s_nop 0
	global_load_lds_dwordx4 v164, s[94:95]
	s_waitcnt vmcnt(8)
	s_barrier
	s_waitcnt lgkmcnt(0)
	v_mfma_f32_16x16x32_bf16 v[62:65], v[130:133], v[208:211], v[62:65]
	ds_read_b128 v[146:149], v241
	v_mfma_f32_16x16x32_bf16 v[58:61], v[138:141], v[208:211], v[58:61]
	v_mfma_f32_16x16x32_bf16 v[54:57], v[130:133], v[216:219], v[54:57]
	ds_read_b128 v[150:153], v241 offset:1024
	v_mfma_f32_16x16x32_bf16 v[50:53], v[138:141], v[216:219], v[50:53]
	v_mfma_f32_16x16x32_bf16 v[42:45], v[130:133], v[224:227], v[42:45]
	ds_read_b128 v[154:157], v241 offset:2048
	v_mfma_f32_16x16x32_bf16 v[34:37], v[138:141], v[224:227], v[34:37]
	v_mfma_f32_16x16x32_bf16 v[26:29], v[130:133], v[232:235], v[26:29]
	ds_read_b128 v[158:161], v241 offset:3072
	v_mfma_f32_16x16x32_bf16 v[18:21], v[138:141], v[232:235], v[18:21]
	v_mfma_f32_16x16x32_bf16 v[62:65], v[134:137], v[212:215], v[62:65]
	ds_read_b128 v[176:179], v241 offset:4096
	v_mfma_f32_16x16x32_bf16 v[58:61], v[142:145], v[212:215], v[58:61]
	v_mfma_f32_16x16x32_bf16 v[54:57], v[134:137], v[220:223], v[54:57]
	ds_read_b128 v[180:183], v241 offset:5120
	v_mfma_f32_16x16x32_bf16 v[50:53], v[142:145], v[220:223], v[50:53]
	v_mfma_f32_16x16x32_bf16 v[42:45], v[134:137], v[228:231], v[42:45]
	ds_read_b128 v[184:187], v241 offset:6144
	v_mfma_f32_16x16x32_bf16 v[34:37], v[142:145], v[228:231], v[34:37]
	v_mfma_f32_16x16x32_bf16 v[26:29], v[134:137], v[246:249], v[26:29]
	ds_read_b128 v[188:191], v241 offset:7168
	v_mfma_f32_16x16x32_bf16 v[18:21], v[142:145], v[246:249], v[18:21]
	s_barrier
	s_add_u32 s50, s50, 0x80080
	s_addc_u32 s51, s51, 0
	s_add_i32 s52, s52, s56
	s_mov_b32 m0, s52
	s_nop 0
	global_load_lds_dwordx4 v162, s[50:51]
	s_add_i32 m0, s52, 0x2000
	s_nop 0
	global_load_lds_dwordx4 v164, s[50:51]
	s_waitcnt vmcnt(10)
	s_barrier
	s_waitcnt lgkmcnt(0)
	v_mfma_f32_16x16x32_bf16 v[46:49], v[192:195], v[208:211], v[46:49]
	ds_read_b128 v[130:133], v240
	v_mfma_f32_16x16x32_bf16 v[38:41], v[200:203], v[208:211], v[38:41]
	v_mfma_f32_16x16x32_bf16 v[30:33], v[192:195], v[216:219], v[30:33]
	v_mfma_f32_16x16x32_bf16 v[22:25], v[200:203], v[216:219], v[22:25]
	v_mfma_f32_16x16x32_bf16 v[14:17], v[192:195], v[224:227], v[14:17]
	ds_read_b128 v[134:137], v240 offset:1024
	v_mfma_f32_16x16x32_bf16 v[10:13], v[200:203], v[224:227], v[10:13]
	v_mfma_f32_16x16x32_bf16 v[6:9], v[192:195], v[232:235], v[6:9]
	v_mfma_f32_16x16x32_bf16 v[2:5], v[200:203], v[232:235], v[2:5]
	v_mfma_f32_16x16x32_bf16 v[46:49], v[196:199], v[212:215], v[46:49]
	ds_read_b128 v[138:141], v240 offset:2048
	v_mfma_f32_16x16x32_bf16 v[38:41], v[204:207], v[212:215], v[38:41]
	v_mfma_f32_16x16x32_bf16 v[30:33], v[196:199], v[220:223], v[30:33]
	v_mfma_f32_16x16x32_bf16 v[22:25], v[204:207], v[220:223], v[22:25]
	v_mfma_f32_16x16x32_bf16 v[14:17], v[196:199], v[228:231], v[14:17]
	ds_read_b128 v[142:145], v240 offset:3072
	v_mfma_f32_16x16x32_bf16 v[10:13], v[204:207], v[228:231], v[10:13]
	v_mfma_f32_16x16x32_bf16 v[6:9], v[196:199], v[246:249], v[6:9]
	v_mfma_f32_16x16x32_bf16 v[2:5], v[204:207], v[246:249], v[2:5]
	s_add_i32 s80, s80, 2
	s_add_u32 s48, s48, 0x100
	s_addc_u32 s49, s49, 0
	s_add_u32 s74, s74, 0x100
	s_addc_u32 s75, s75, 0
	s_cmp_gt_u32 s80, s87
	s_cbranch_scc0 .LBB0_1098
	s_barrier

.LBB0_1296:
	v_add_u32_e32 v154, 0x18000, v173
	v_add_u32_e32 v155, 0x1c000, v173
	ds_read_b128 v[126:129], v175
	ds_read_b128 v[134:137], v175 offset:1024
	ds_read_b128 v[138:141], v175 offset:2048
	ds_read_b128 v[142:145], v175 offset:3072
	ds_read_b128 v[158:161], v176
	ds_read_b128 v[178:181], v176 offset:1024
	ds_read_b128 v[182:185], v176 offset:2048
	ds_read_b128 v[186:189], v176 offset:3072
	ds_read_b128 v[190:193], v176 offset:4096
	ds_read_b128 v[194:197], v176 offset:5120
	ds_read_b128 v[198:201], v176 offset:6144
	ds_read_b128 v[202:205], v176 offset:7168
	s_add_u32 s28, s28, 0x160080
	s_addc_u32 s29, s29, 0
	s_add_u32 s58, s30, 0x100
	s_addc_u32 s59, s31, 0
	s_mov_b32 s60, -2
	s_add_u32 s30, s28, 0xffea0080
	s_addc_u32 s31, s29, -1
	s_cmpk_eq_i32 s60, 0x54
	s_cselect_b32 s35, s7, s31
	s_cselect_b32 s34, s6, s30
	s_cselect_b32 s31, s9, s59
	s_cselect_b32 s30, s8, s58
	s_add_i32 m0, s43, 0xc000
	s_nop 0
	global_load_lds_dwordx4 v150, s[28:29]
	s_add_i32 m0, s43, 0xe000
	s_nop 0
	global_load_lds_dwordx4 v152, s[28:29]
	s_waitcnt vmcnt(10)
	s_barrier
	s_waitcnt lgkmcnt(0)
	v_mfma_f32_16x16x32_bf16 v[130:133], v[126:129], v[158:161], 0
	ds_read_b128 v[206:209], v177
	v_mfma_f32_16x16x32_bf16 v[122:125], v[138:141], v[158:161], 0
	v_mfma_f32_16x16x32_bf16 v[118:121], v[126:129], v[182:185], 0
	v_mfma_f32_16x16x32_bf16 v[114:117], v[138:141], v[182:185], 0
	v_mfma_f32_16x16x32_bf16 v[102:105], v[126:129], v[190:193], 0
	ds_read_b128 v[210:213], v177 offset:1024
	v_mfma_f32_16x16x32_bf16 v[98:101], v[138:141], v[190:193], 0
	v_mfma_f32_16x16x32_bf16 v[86:89], v[126:129], v[198:201], 0
	v_mfma_f32_16x16x32_bf16 v[82:85], v[138:141], v[198:201], 0
	v_mfma_f32_16x16x32_bf16 v[130:133], v[134:137], v[178:181], v[130:133]
	ds_read_b128 v[214:217], v177 offset:2048
	v_mfma_f32_16x16x32_bf16 v[122:125], v[142:145], v[178:181], v[122:125]
	v_mfma_f32_16x16x32_bf16 v[118:121], v[134:137], v[186:189], v[118:121]
	v_mfma_f32_16x16x32_bf16 v[114:117], v[142:145], v[186:189], v[114:117]
	v_mfma_f32_16x16x32_bf16 v[102:105], v[134:137], v[194:197], v[102:105]
	ds_read_b128 v[218:221], v177 offset:3072
	v_mfma_f32_16x16x32_bf16 v[98:101], v[142:145], v[194:197], v[98:101]
	v_mfma_f32_16x16x32_bf16 v[86:89], v[134:137], v[202:205], v[86:89]
	v_mfma_f32_16x16x32_bf16 v[82:85], v[142:145], v[202:205], v[82:85]
	s_barrier
	s_add_i32 s61, s51, s40
	s_add_u32 s96, s30, 0x80
	s_addc_u32 s97, s31, 0
	s_mov_b32 m0, s61
	s_nop 0
	global_load_lds_dwordx4 v146, s[30:31]
	s_add_i32 m0, s61, 0x2000
	s_nop 0
	global_load_lds_dwordx4 v148, s[30:31]
	s_waitcnt vmcnt(10)
	s_barrier
	s_waitcnt lgkmcnt(0)
	v_mfma_f32_16x16x32_bf16 v[110:113], v[206:209], v[158:161], 0
	ds_read_b128 v[226:229], v176 offset:16384
	v_mfma_f32_16x16x32_bf16 v[106:109], v[214:217], v[158:161], 0
	v_mfma_f32_16x16x32_bf16 v[94:97], v[206:209], v[182:185], 0
	ds_read_b128 v[230:233], v176 offset:17408
	v_mfma_f32_16x16x32_bf16 v[90:93], v[214:217], v[182:185], 0
	v_mfma_f32_16x16x32_bf16 v[78:81], v[206:209], v[190:193], 0
	ds_read_b128 v[234:237], v176 offset:18432
	v_mfma_f32_16x16x32_bf16 v[74:77], v[214:217], v[190:193], 0
	v_mfma_f32_16x16x32_bf16 v[70:73], v[206:209], v[198:201], 0
	ds_read_b128 v[238:241], v176 offset:19456
	v_mfma_f32_16x16x32_bf16 v[66:69], v[214:217], v[198:201], 0
	v_mfma_f32_16x16x32_bf16 v[110:113], v[210:213], v[178:181], v[110:113]
	ds_read_b128 v[242:245], v176 offset:20480
	v_mfma_f32_16x16x32_bf16 v[106:109], v[218:221], v[178:181], v[106:109]
	v_mfma_f32_16x16x32_bf16 v[94:97], v[210:213], v[186:189], v[94:97]
	ds_read_b128 v[246:249], v176 offset:21504
	v_mfma_f32_16x16x32_bf16 v[90:93], v[218:221], v[186:189], v[90:93]
	v_mfma_f32_16x16x32_bf16 v[78:81], v[210:213], v[194:197], v[78:81]
	ds_read_b128 v[250:253], v176 offset:22528
	v_mfma_f32_16x16x32_bf16 v[74:77], v[218:221], v[194:197], v[74:77]
	v_mfma_f32_16x16x32_bf16 v[70:73], v[210:213], v[202:205], v[70:73]
	ds_read_b128 v[222:225], v176 offset:23552
	v_mfma_f32_16x16x32_bf16 v[66:69], v[218:221], v[202:205], v[66:69]
	s_barrier
	s_mov_b32 m0, s43
	s_add_u32 s94, s34, 0x80
	s_addc_u32 s95, s35, 0
	global_load_lds_dwordx4 v146, s[34:35]
	s_mov_b32 m0, s44
	s_nop 0
	global_load_lds_dwordx4 v148, s[34:35]
	s_waitcnt vmcnt(8)
	s_barrier
	s_waitcnt lgkmcnt(0)
	v_mfma_f32_16x16x32_bf16 v[62:65], v[126:129], v[226:229], 0
	ds_read_b128 v[158:161], v176 offset:32768
	v_mfma_f32_16x16x32_bf16 v[58:61], v[138:141], v[226:229], 0
	v_mfma_f32_16x16x32_bf16 v[54:57], v[126:129], v[234:237], 0
	ds_read_b128 v[178:181], v176 offset:33792
	v_mfma_f32_16x16x32_bf16 v[46:49], v[138:141], v[234:237], 0
	v_mfma_f32_16x16x32_bf16 v[38:41], v[126:129], v[242:245], 0
	ds_read_b128 v[182:185], v176 offset:34816
	v_mfma_f32_16x16x32_bf16 v[30:33], v[138:141], v[242:245], 0
	v_mfma_f32_16x16x32_bf16 v[22:25], v[126:129], v[250:253], 0
	ds_read_b128 v[186:189], v176 offset:35840
	v_mfma_f32_16x16x32_bf16 v[14:17], v[138:141], v[250:253], 0
	v_mfma_f32_16x16x32_bf16 v[62:65], v[134:137], v[230:233], v[62:65]
	ds_read_b128 v[190:193], v176 offset:36864
	v_mfma_f32_16x16x32_bf16 v[58:61], v[142:145], v[230:233], v[58:61]
	v_mfma_f32_16x16x32_bf16 v[54:57], v[134:137], v[238:241], v[54:57]
	ds_read_b128 v[194:197], v176 offset:37888
	v_mfma_f32_16x16x32_bf16 v[46:49], v[142:145], v[238:241], v[46:49]
	v_mfma_f32_16x16x32_bf16 v[38:41], v[134:137], v[246:249], v[38:41]
	ds_read_b128 v[198:201], v176 offset:38912
	v_mfma_f32_16x16x32_bf16 v[30:33], v[142:145], v[246:249], v[30:33]
	v_mfma_f32_16x16x32_bf16 v[22:25], v[134:137], v[222:225], v[22:25]
	ds_read_b128 v[202:205], v176 offset:39936
	v_mfma_f32_16x16x32_bf16 v[14:17], v[142:145], v[222:225], v[14:17]
	s_barrier
	s_add_u32 s62, s30, 0x160000
	s_addc_u32 s63, s31, 0
	s_add_i32 s61, s52, s40
	s_mov_b32 m0, s61
	s_nop 0
	global_load_lds_dwordx4 v146, s[62:63]
	s_add_i32 m0, s61, 0x2000
	s_nop 0
	global_load_lds_dwordx4 v148, s[62:63]
	s_waitcnt vmcnt(10)
	s_barrier
	s_waitcnt lgkmcnt(0)
	v_mfma_f32_16x16x32_bf16 v[50:53], v[206:209], v[226:229], 0
	ds_read_b128 v[126:129], v154
	v_mfma_f32_16x16x32_bf16 v[42:45], v[214:217], v[226:229], 0
	v_mfma_f32_16x16x32_bf16 v[34:37], v[206:209], v[234:237], 0
	v_mfma_f32_16x16x32_bf16 v[26:29], v[214:217], v[234:237], 0
	v_mfma_f32_16x16x32_bf16 v[18:21], v[206:209], v[242:245], 0
	ds_read_b128 v[134:137], v154 offset:1024
	v_mfma_f32_16x16x32_bf16 v[10:13], v[214:217], v[242:245], 0
	v_mfma_f32_16x16x32_bf16 v[6:9], v[206:209], v[250:253], 0
	v_mfma_f32_16x16x32_bf16 v[2:5], v[214:217], v[250:253], 0
	v_mfma_f32_16x16x32_bf16 v[50:53], v[210:213], v[230:233], v[50:53]
	ds_read_b128 v[138:141], v154 offset:2048
	v_mfma_f32_16x16x32_bf16 v[42:45], v[218:221], v[230:233], v[42:45]
	v_mfma_f32_16x16x32_bf16 v[34:37], v[210:213], v[238:241], v[34:37]
	v_mfma_f32_16x16x32_bf16 v[26:29], v[218:221], v[238:241], v[26:29]
	v_mfma_f32_16x16x32_bf16 v[18:21], v[210:213], v[246:249], v[18:21]
	ds_read_b128 v[142:145], v154 offset:3072
	v_mfma_f32_16x16x32_bf16 v[10:13], v[218:221], v[246:249], v[10:13]
	v_mfma_f32_16x16x32_bf16 v[6:9], v[210:213], v[222:225], v[6:9]
	v_mfma_f32_16x16x32_bf16 v[2:5], v[218:221], v[222:225], v[2:5]
	s_barrier
	s_add_i32 s61, 0, 0x18000
	s_add_u32 s34, s34, 0x160000
	s_addc_u32 s35, s35, 0
	s_mov_b32 m0, s45
	s_nop 0
	global_load_lds_dwordx4 v146, s[34:35]
	s_mov_b32 m0, s46
	s_nop 0
	global_load_lds_dwordx4 v148, s[34:35]
	s_waitcnt vmcnt(10)
	s_barrier
	s_waitcnt lgkmcnt(0)
	v_mfma_f32_16x16x32_bf16 v[130:133], v[126:129], v[158:161], v[130:133]
	ds_read_b128 v[206:209], v155
	v_mfma_f32_16x16x32_bf16 v[122:125], v[138:141], v[158:161], v[122:125]
	v_mfma_f32_16x16x32_bf16 v[118:121], v[126:129], v[182:185], v[118:121]
	v_mfma_f32_16x16x32_bf16 v[114:117], v[138:141], v[182:185], v[114:117]
	v_mfma_f32_16x16x32_bf16 v[102:105], v[126:129], v[190:193], v[102:105]
	ds_read_b128 v[210:213], v155 offset:1024
	v_mfma_f32_16x16x32_bf16 v[98:101], v[138:141], v[190:193], v[98:101]
	v_mfma_f32_16x16x32_bf16 v[86:89], v[126:129], v[198:201], v[86:89]
	v_mfma_f32_16x16x32_bf16 v[82:85], v[138:141], v[198:201], v[82:85]
	v_mfma_f32_16x16x32_bf16 v[130:133], v[134:137], v[178:181], v[130:133]
	ds_read_b128 v[214:217], v155 offset:2048
	v_mfma_f32_16x16x32_bf16 v[122:125], v[142:145], v[178:181], v[122:125]
	v_mfma_f32_16x16x32_bf16 v[118:121], v[134:137], v[186:189], v[118:121]
	v_mfma_f32_16x16x32_bf16 v[114:117], v[142:145], v[186:189], v[114:117]
	v_mfma_f32_16x16x32_bf16 v[102:105], v[134:137], v[194:197], v[102:105]
	ds_read_b128 v[218:221], v155 offset:3072
	v_mfma_f32_16x16x32_bf16 v[98:101], v[142:145], v[194:197], v[98:101]
	v_mfma_f32_16x16x32_bf16 v[86:89], v[134:137], v[202:205], v[86:89]
	v_mfma_f32_16x16x32_bf16 v[82:85], v[142:145], v[202:205], v[82:85]
	s_barrier
	s_add_i32 s84, 0, 0x1c000
	s_add_i32 s85, s61, s40
	s_mov_b32 m0, s85
	s_nop 0
	global_load_lds_dwordx4 v146, s[96:97]
	s_add_i32 m0, s85, 0x2000
	s_nop 0
	global_load_lds_dwordx4 v148, s[96:97]
	s_waitcnt vmcnt(10)
	s_barrier
	s_waitcnt lgkmcnt(0)
	v_mfma_f32_16x16x32_bf16 v[110:113], v[206:209], v[158:161], v[110:113]
	ds_read_b128 v[226:229], v176 offset:49152
	v_mfma_f32_16x16x32_bf16 v[106:109], v[214:217], v[158:161], v[106:109]
	v_mfma_f32_16x16x32_bf16 v[94:97], v[206:209], v[182:185], v[94:97]
	ds_read_b128 v[230:233], v176 offset:50176
	v_mfma_f32_16x16x32_bf16 v[90:93], v[214:217], v[182:185], v[90:93]
	v_mfma_f32_16x16x32_bf16 v[78:81], v[206:209], v[190:193], v[78:81]
	ds_read_b128 v[234:237], v176 offset:51200
	v_mfma_f32_16x16x32_bf16 v[74:77], v[214:217], v[190:193], v[74:77]
	v_mfma_f32_16x16x32_bf16 v[70:73], v[206:209], v[198:201], v[70:73]
	ds_read_b128 v[238:241], v176 offset:52224
	v_mfma_f32_16x16x32_bf16 v[66:69], v[214:217], v[198:201], v[66:69]
	v_mfma_f32_16x16x32_bf16 v[110:113], v[210:213], v[178:181], v[110:113]
	ds_read_b128 v[242:245], v176 offset:53248
	v_mfma_f32_16x16x32_bf16 v[106:109], v[218:221], v[178:181], v[106:109]
	v_mfma_f32_16x16x32_bf16 v[94:97], v[210:213], v[186:189], v[94:97]
	ds_read_b128 v[246:249], v176 offset:54272
	v_mfma_f32_16x16x32_bf16 v[90:93], v[218:221], v[186:189], v[90:93]
	v_mfma_f32_16x16x32_bf16 v[78:81], v[210:213], v[194:197], v[78:81]
	ds_read_b128 v[250:253], v176 offset:55296
	v_mfma_f32_16x16x32_bf16 v[74:77], v[218:221], v[194:197], v[74:77]
	v_mfma_f32_16x16x32_bf16 v[70:73], v[210:213], v[202:205], v[70:73]
	ds_read_b128 v[222:225], v176 offset:56320
	v_mfma_f32_16x16x32_bf16 v[66:69], v[218:221], v[202:205], v[66:69]
	s_barrier
	s_mov_b32 m0, s48
	s_nop 0
	global_load_lds_dwordx4 v146, s[94:95]
	s_mov_b32 m0, s49
	s_nop 0
	global_load_lds_dwordx4 v148, s[94:95]
	s_waitcnt vmcnt(8)
	s_barrier
	s_waitcnt lgkmcnt(0)
	v_mfma_f32_16x16x32_bf16 v[62:65], v[126:129], v[226:229], v[62:65]
	ds_read_b128 v[158:161], v176
	v_mfma_f32_16x16x32_bf16 v[58:61], v[138:141], v[226:229], v[58:61]
	v_mfma_f32_16x16x32_bf16 v[54:57], v[126:129], v[234:237], v[54:57]
	ds_read_b128 v[178:181], v176 offset:1024
	v_mfma_f32_16x16x32_bf16 v[46:49], v[138:141], v[234:237], v[46:49]
	v_mfma_f32_16x16x32_bf16 v[38:41], v[126:129], v[242:245], v[38:41]
	ds_read_b128 v[182:185], v176 offset:2048
	v_mfma_f32_16x16x32_bf16 v[30:33], v[138:141], v[242:245], v[30:33]
	v_mfma_f32_16x16x32_bf16 v[22:25], v[126:129], v[250:253], v[22:25]
	ds_read_b128 v[186:189], v176 offset:3072
	v_mfma_f32_16x16x32_bf16 v[14:17], v[138:141], v[250:253], v[14:17]
	v_mfma_f32_16x16x32_bf16 v[62:65], v[134:137], v[230:233], v[62:65]
	ds_read_b128 v[190:193], v176 offset:4096
	v_mfma_f32_16x16x32_bf16 v[58:61], v[142:145], v[230:233], v[58:61]
	v_mfma_f32_16x16x32_bf16 v[54:57], v[134:137], v[238:241], v[54:57]
	ds_read_b128 v[194:197], v176 offset:5120
	v_mfma_f32_16x16x32_bf16 v[46:49], v[142:145], v[238:241], v[46:49]
	v_mfma_f32_16x16x32_bf16 v[38:41], v[134:137], v[246:249], v[38:41]
	ds_read_b128 v[198:201], v176 offset:6144
	v_mfma_f32_16x16x32_bf16 v[30:33], v[142:145], v[246:249], v[30:33]
	v_mfma_f32_16x16x32_bf16 v[22:25], v[134:137], v[222:225], v[22:25]
	ds_read_b128 v[202:205], v176 offset:7168
	v_mfma_f32_16x16x32_bf16 v[14:17], v[142:145], v[222:225], v[14:17]
	s_barrier
	s_add_u32 s30, s30, 0x160080
	s_addc_u32 s31, s31, 0
	s_add_i32 s84, s84, s40
	s_mov_b32 m0, s84
	s_nop 0
	global_load_lds_dwordx4 v146, s[30:31]
	s_add_i32 m0, s84, 0x2000
	s_nop 0
	global_load_lds_dwordx4 v148, s[30:31]
	s_waitcnt vmcnt(10)
	s_barrier
	s_waitcnt lgkmcnt(0)
	v_mfma_f32_16x16x32_bf16 v[50:53], v[206:209], v[226:229], v[50:53]
	ds_read_b128 v[126:129], v175
	v_mfma_f32_16x16x32_bf16 v[42:45], v[214:217], v[226:229], v[42:45]
	v_mfma_f32_16x16x32_bf16 v[34:37], v[206:209], v[234:237], v[34:37]
	v_mfma_f32_16x16x32_bf16 v[26:29], v[214:217], v[234:237], v[26:29]
	v_mfma_f32_16x16x32_bf16 v[18:21], v[206:209], v[242:245], v[18:21]
	ds_read_b128 v[134:137], v175 offset:1024
	v_mfma_f32_16x16x32_bf16 v[10:13], v[214:217], v[242:245], v[10:13]
	v_mfma_f32_16x16x32_bf16 v[6:9], v[206:209], v[250:253], v[6:9]
	v_mfma_f32_16x16x32_bf16 v[2:5], v[214:217], v[250:253], v[2:5]
	v_mfma_f32_16x16x32_bf16 v[50:53], v[210:213], v[230:233], v[50:53]
	ds_read_b128 v[138:141], v175 offset:2048
	v_mfma_f32_16x16x32_bf16 v[42:45], v[218:221], v[230:233], v[42:45]
	v_mfma_f32_16x16x32_bf16 v[34:37], v[210:213], v[238:241], v[34:37]
	v_mfma_f32_16x16x32_bf16 v[26:29], v[218:221], v[238:241], v[26:29]
	v_mfma_f32_16x16x32_bf16 v[18:21], v[210:213], v[246:249], v[18:21]
	ds_read_b128 v[142:145], v175 offset:3072
	v_mfma_f32_16x16x32_bf16 v[10:13], v[218:221], v[246:249], v[10:13]
	v_mfma_f32_16x16x32_bf16 v[6:9], v[210:213], v[222:225], v[6:9]
	v_mfma_f32_16x16x32_bf16 v[2:5], v[218:221], v[222:225], v[2:5]
	s_add_i32 s60, s60, 2
	s_add_u32 s28, s28, 0x100
	s_addc_u32 s29, s29, 0
	s_add_u32 s58, s58, 0x100
	s_addc_u32 s59, s59, 0
	s_cmpk_gt_u32 s60, 0x55
	s_cbranch_scc0 .LBB0_1297
	s_barrier
	s_branch .Lp10_loop_exit
.LBB0_1297:
	s_barrier
	s_add_u32 s30, s28, 0xffea0080
	s_addc_u32 s31, s29, -1
	s_cmpk_eq_i32 s60, 0x54
	s_cselect_b32 s35, s7, s31
	s_cselect_b32 s34, s6, s30
	s_cselect_b32 s31, s9, s59
	s_cselect_b32 s30, s8, s58
	s_add_i32 m0, s43, 0xc000
	s_nop 0
	global_load_lds_dwordx4 v150, s[28:29]
	s_add_i32 m0, s43, 0xe000
	s_nop 0
	global_load_lds_dwordx4 v152, s[28:29]
	s_waitcnt vmcnt(10)
	s_barrier
	s_waitcnt lgkmcnt(0)
	v_mfma_f32_16x16x32_bf16 v[130:133], v[126:129], v[158:161], v[130:133]
	ds_read_b128 v[206:209], v177
	v_mfma_f32_16x16x32_bf16 v[122:125], v[138:141], v[158:161], v[122:125]
	v_mfma_f32_16x16x32_bf16 v[118:121], v[126:129], v[182:185], v[118:121]
	v_mfma_f32_16x16x32_bf16 v[114:117], v[138:141], v[182:185], v[114:117]
	v_mfma_f32_16x16x32_bf16 v[102:105], v[126:129], v[190:193], v[102:105]
	ds_read_b128 v[210:213], v177 offset:1024
	v_mfma_f32_16x16x32_bf16 v[98:101], v[138:141], v[190:193], v[98:101]
	v_mfma_f32_16x16x32_bf16 v[86:89], v[126:129], v[198:201], v[86:89]
	v_mfma_f32_16x16x32_bf16 v[82:85], v[138:141], v[198:201], v[82:85]
	v_mfma_f32_16x16x32_bf16 v[130:133], v[134:137], v[178:181], v[130:133]
	ds_read_b128 v[214:217], v177 offset:2048
	v_mfma_f32_16x16x32_bf16 v[122:125], v[142:145], v[178:181], v[122:125]
	v_mfma_f32_16x16x32_bf16 v[118:121], v[134:137], v[186:189], v[118:121]
	v_mfma_f32_16x16x32_bf16 v[114:117], v[142:145], v[186:189], v[114:117]
	v_mfma_f32_16x16x32_bf16 v[102:105], v[134:137], v[194:197], v[102:105]
	ds_read_b128 v[218:221], v177 offset:3072
	v_mfma_f32_16x16x32_bf16 v[98:101], v[142:145], v[194:197], v[98:101]
	v_mfma_f32_16x16x32_bf16 v[86:89], v[134:137], v[202:205], v[86:89]
	v_mfma_f32_16x16x32_bf16 v[82:85], v[142:145], v[202:205], v[82:85]
	s_barrier
	s_add_i32 s61, s51, s40
	s_add_u32 s96, s30, 0x80
	s_addc_u32 s97, s31, 0
	s_mov_b32 m0, s61
	s_nop 0
	global_load_lds_dwordx4 v146, s[30:31]
	s_add_i32 m0, s61, 0x2000
	s_nop 0
	global_load_lds_dwordx4 v148, s[30:31]
	s_waitcnt vmcnt(10)
	s_barrier
	s_waitcnt lgkmcnt(0)
	v_mfma_f32_16x16x32_bf16 v[110:113], v[206:209], v[158:161], v[110:113]
	ds_read_b128 v[226:229], v176 offset:16384
	v_mfma_f32_16x16x32_bf16 v[106:109], v[214:217], v[158:161], v[106:109]
	v_mfma_f32_16x16x32_bf16 v[94:97], v[206:209], v[182:185], v[94:97]
	ds_read_b128 v[230:233], v176 offset:17408
	v_mfma_f32_16x16x32_bf16 v[90:93], v[214:217], v[182:185], v[90:93]
	v_mfma_f32_16x16x32_bf16 v[78:81], v[206:209], v[190:193], v[78:81]
	ds_read_b128 v[234:237], v176 offset:18432
	v_mfma_f32_16x16x32_bf16 v[74:77], v[214:217], v[190:193], v[74:77]
	v_mfma_f32_16x16x32_bf16 v[70:73], v[206:209], v[198:201], v[70:73]
	ds_read_b128 v[238:241], v176 offset:19456
	v_mfma_f32_16x16x32_bf16 v[66:69], v[214:217], v[198:201], v[66:69]
	v_mfma_f32_16x16x32_bf16 v[110:113], v[210:213], v[178:181], v[110:113]
	ds_read_b128 v[242:245], v176 offset:20480
	v_mfma_f32_16x16x32_bf16 v[106:109], v[218:221], v[178:181], v[106:109]
	v_mfma_f32_16x16x32_bf16 v[94:97], v[210:213], v[186:189], v[94:97]
	ds_read_b128 v[246:249], v176 offset:21504
	v_mfma_f32_16x16x32_bf16 v[90:93], v[218:221], v[186:189], v[90:93]
	v_mfma_f32_16x16x32_bf16 v[78:81], v[210:213], v[194:197], v[78:81]
	ds_read_b128 v[250:253], v176 offset:22528
	v_mfma_f32_16x16x32_bf16 v[74:77], v[218:221], v[194:197], v[74:77]
	v_mfma_f32_16x16x32_bf16 v[70:73], v[210:213], v[202:205], v[70:73]
	ds_read_b128 v[222:225], v176 offset:23552
	v_mfma_f32_16x16x32_bf16 v[66:69], v[218:221], v[202:205], v[66:69]
	s_barrier
	s_mov_b32 m0, s43
	s_add_u32 s94, s34, 0x80
	s_addc_u32 s95, s35, 0
	global_load_lds_dwordx4 v146, s[34:35]
	s_mov_b32 m0, s44
	s_nop 0
	global_load_lds_dwordx4 v148, s[34:35]
	s_waitcnt vmcnt(8)
	s_barrier
	s_waitcnt lgkmcnt(0)
	v_mfma_f32_16x16x32_bf16 v[62:65], v[126:129], v[226:229], v[62:65]
	ds_read_b128 v[158:161], v176 offset:32768
	v_mfma_f32_16x16x32_bf16 v[58:61], v[138:141], v[226:229], v[58:61]
	v_mfma_f32_16x16x32_bf16 v[54:57], v[126:129], v[234:237], v[54:57]
	ds_read_b128 v[178:181], v176 offset:33792
	v_mfma_f32_16x16x32_bf16 v[46:49], v[138:141], v[234:237], v[46:49]
	v_mfma_f32_16x16x32_bf16 v[38:41], v[126:129], v[242:245], v[38:41]
	ds_read_b128 v[182:185], v176 offset:34816
	v_mfma_f32_16x16x32_bf16 v[30:33], v[138:141], v[242:245], v[30:33]
	v_mfma_f32_16x16x32_bf16 v[22:25], v[126:129], v[250:253], v[22:25]
	ds_read_b128 v[186:189], v176 offset:35840
	v_mfma_f32_16x16x32_bf16 v[14:17], v[138:141], v[250:253], v[14:17]
	v_mfma_f32_16x16x32_bf16 v[62:65], v[134:137], v[230:233], v[62:65]
	ds_read_b128 v[190:193], v176 offset:36864
	v_mfma_f32_16x16x32_bf16 v[58:61], v[142:145], v[230:233], v[58:61]
	v_mfma_f32_16x16x32_bf16 v[54:57], v[134:137], v[238:241], v[54:57]
	ds_read_b128 v[194:197], v176 offset:37888
	v_mfma_f32_16x16x32_bf16 v[46:49], v[142:145], v[238:241], v[46:49]
	v_mfma_f32_16x16x32_bf16 v[38:41], v[134:137], v[246:249], v[38:41]
	ds_read_b128 v[198:201], v176 offset:38912
	v_mfma_f32_16x16x32_bf16 v[30:33], v[142:145], v[246:249], v[30:33]
	v_mfma_f32_16x16x32_bf16 v[22:25], v[134:137], v[222:225], v[22:25]
	ds_read_b128 v[202:205], v176 offset:39936
	v_mfma_f32_16x16x32_bf16 v[14:17], v[142:145], v[222:225], v[14:17]
	s_barrier
	s_add_u32 s62, s30, 0x160000
	s_addc_u32 s63, s31, 0
	s_add_i32 s61, s52, s40
	s_mov_b32 m0, s61
	s_nop 0
	global_load_lds_dwordx4 v146, s[62:63]
	s_add_i32 m0, s61, 0x2000
	s_nop 0
	global_load_lds_dwordx4 v148, s[62:63]
	s_waitcnt vmcnt(10)
	s_barrier
	s_waitcnt lgkmcnt(0)
	v_mfma_f32_16x16x32_bf16 v[50:53], v[206:209], v[226:229], v[50:53]
	ds_read_b128 v[126:129], v154
	v_mfma_f32_16x16x32_bf16 v[42:45], v[214:217], v[226:229], v[42:45]
	v_mfma_f32_16x16x32_bf16 v[34:37], v[206:209], v[234:237], v[34:37]
	v_mfma_f32_16x16x32_bf16 v[26:29], v[214:217], v[234:237], v[26:29]
	v_mfma_f32_16x16x32_bf16 v[18:21], v[206:209], v[242:245], v[18:21]
	ds_read_b128 v[134:137], v154 offset:1024
	v_mfma_f32_16x16x32_bf16 v[10:13], v[214:217], v[242:245], v[10:13]
	v_mfma_f32_16x16x32_bf16 v[6:9], v[206:209], v[250:253], v[6:9]
	v_mfma_f32_16x16x32_bf16 v[2:5], v[214:217], v[250:253], v[2:5]
	v_mfma_f32_16x16x32_bf16 v[50:53], v[210:213], v[230:233], v[50:53]
	ds_read_b128 v[138:141], v154 offset:2048
	v_mfma_f32_16x16x32_bf16 v[42:45], v[218:221], v[230:233], v[42:45]
	v_mfma_f32_16x16x32_bf16 v[34:37], v[210:213], v[238:241], v[34:37]
	v_mfma_f32_16x16x32_bf16 v[26:29], v[218:221], v[238:241], v[26:29]
	v_mfma_f32_16x16x32_bf16 v[18:21], v[210:213], v[246:249], v[18:21]
	ds_read_b128 v[142:145], v154 offset:3072
	v_mfma_f32_16x16x32_bf16 v[10:13], v[218:221], v[246:249], v[10:13]
	v_mfma_f32_16x16x32_bf16 v[6:9], v[210:213], v[222:225], v[6:9]
	v_mfma_f32_16x16x32_bf16 v[2:5], v[218:221], v[222:225], v[2:5]
	s_barrier
	s_add_i32 s61, 0, 0x18000
	s_add_u32 s34, s34, 0x160000
	s_addc_u32 s35, s35, 0
	s_mov_b32 m0, s45
	s_nop 0
	global_load_lds_dwordx4 v146, s[34:35]
	s_mov_b32 m0, s46
	s_nop 0
	global_load_lds_dwordx4 v148, s[34:35]
	s_waitcnt vmcnt(10)
	s_barrier
	s_waitcnt lgkmcnt(0)
	v_mfma_f32_16x16x32_bf16 v[130:133], v[126:129], v[158:161], v[130:133]
	ds_read_b128 v[206:209], v155
	v_mfma_f32_16x16x32_bf16 v[122:125], v[138:141], v[158:161], v[122:125]
	v_mfma_f32_16x16x32_bf16 v[118:121], v[126:129], v[182:185], v[118:121]
	v_mfma_f32_16x16x32_bf16 v[114:117], v[138:141], v[182:185], v[114:117]
	v_mfma_f32_16x16x32_bf16 v[102:105], v[126:129], v[190:193], v[102:105]
	ds_read_b128 v[210:213], v155 offset:1024
	v_mfma_f32_16x16x32_bf16 v[98:101], v[138:141], v[190:193], v[98:101]
	v_mfma_f32_16x16x32_bf16 v[86:89], v[126:129], v[198:201], v[86:89]
	v_mfma_f32_16x16x32_bf16 v[82:85], v[138:141], v[198:201], v[82:85]
	v_mfma_f32_16x16x32_bf16 v[130:133], v[134:137], v[178:181], v[130:133]
	ds_read_b128 v[214:217], v155 offset:2048
	v_mfma_f32_16x16x32_bf16 v[122:125], v[142:145], v[178:181], v[122:125]
	v_mfma_f32_16x16x32_bf16 v[118:121], v[134:137], v[186:189], v[118:121]
	v_mfma_f32_16x16x32_bf16 v[114:117], v[142:145], v[186:189], v[114:117]
	v_mfma_f32_16x16x32_bf16 v[102:105], v[134:137], v[194:197], v[102:105]
	ds_read_b128 v[218:221], v155 offset:3072
	v_mfma_f32_16x16x32_bf16 v[98:101], v[142:145], v[194:197], v[98:101]
	v_mfma_f32_16x16x32_bf16 v[86:89], v[134:137], v[202:205], v[86:89]
	v_mfma_f32_16x16x32_bf16 v[82:85], v[142:145], v[202:205], v[82:85]
	s_barrier
	s_add_i32 s84, 0, 0x1c000
	s_add_i32 s85, s61, s40
	s_mov_b32 m0, s85
	s_nop 0
	global_load_lds_dwordx4 v146, s[96:97]
	s_add_i32 m0, s85, 0x2000
	s_nop 0
	global_load_lds_dwordx4 v148, s[96:97]
	s_waitcnt vmcnt(10)
	s_barrier
	s_waitcnt lgkmcnt(0)
	v_mfma_f32_16x16x32_bf16 v[110:113], v[206:209], v[158:161], v[110:113]
	ds_read_b128 v[226:229], v176 offset:49152
	v_mfma_f32_16x16x32_bf16 v[106:109], v[214:217], v[158:161], v[106:109]
	v_mfma_f32_16x16x32_bf16 v[94:97], v[206:209], v[182:185], v[94:97]
	ds_read_b128 v[230:233], v176 offset:50176
	v_mfma_f32_16x16x32_bf16 v[90:93], v[214:217], v[182:185], v[90:93]
	v_mfma_f32_16x16x32_bf16 v[78:81], v[206:209], v[190:193], v[78:81]
	ds_read_b128 v[234:237], v176 offset:51200
	v_mfma_f32_16x16x32_bf16 v[74:77], v[214:217], v[190:193], v[74:77]
	v_mfma_f32_16x16x32_bf16 v[70:73], v[206:209], v[198:201], v[70:73]
	ds_read_b128 v[238:241], v176 offset:52224
	v_mfma_f32_16x16x32_bf16 v[66:69], v[214:217], v[198:201], v[66:69]
	v_mfma_f32_16x16x32_bf16 v[110:113], v[210:213], v[178:181], v[110:113]
	ds_read_b128 v[242:245], v176 offset:53248
	v_mfma_f32_16x16x32_bf16 v[106:109], v[218:221], v[178:181], v[106:109]
	v_mfma_f32_16x16x32_bf16 v[94:97], v[210:213], v[186:189], v[94:97]
	ds_read_b128 v[246:249], v176 offset:54272
	v_mfma_f32_16x16x32_bf16 v[90:93], v[218:221], v[186:189], v[90:93]
	v_mfma_f32_16x16x32_bf16 v[78:81], v[210:213], v[194:197], v[78:81]
	ds_read_b128 v[250:253], v176 offset:55296
	v_mfma_f32_16x16x32_bf16 v[74:77], v[218:221], v[194:197], v[74:77]
	v_mfma_f32_16x16x32_bf16 v[70:73], v[210:213], v[202:205], v[70:73]
	ds_read_b128 v[222:225], v176 offset:56320
	v_mfma_f32_16x16x32_bf16 v[66:69], v[218:221], v[202:205], v[66:69]
	s_barrier
	s_mov_b32 m0, s48
	s_nop 0
	global_load_lds_dwordx4 v146, s[94:95]
	s_mov_b32 m0, s49
	s_nop 0
	global_load_lds_dwordx4 v148, s[94:95]
	s_waitcnt vmcnt(8)
	s_barrier
	s_waitcnt lgkmcnt(0)
	v_mfma_f32_16x16x32_bf16 v[62:65], v[126:129], v[226:229], v[62:65]
	ds_read_b128 v[158:161], v176
	v_mfma_f32_16x16x32_bf16 v[58:61], v[138:141], v[226:229], v[58:61]
	v_mfma_f32_16x16x32_bf16 v[54:57], v[126:129], v[234:237], v[54:57]
	ds_read_b128 v[178:181], v176 offset:1024
	v_mfma_f32_16x16x32_bf16 v[46:49], v[138:141], v[234:237], v[46:49]
	v_mfma_f32_16x16x32_bf16 v[38:41], v[126:129], v[242:245], v[38:41]
	ds_read_b128 v[182:185], v176 offset:2048
	v_mfma_f32_16x16x32_bf16 v[30:33], v[138:141], v[242:245], v[30:33]
	v_mfma_f32_16x16x32_bf16 v[22:25], v[126:129], v[250:253], v[22:25]
	ds_read_b128 v[186:189], v176 offset:3072
	v_mfma_f32_16x16x32_bf16 v[14:17], v[138:141], v[250:253], v[14:17]
	v_mfma_f32_16x16x32_bf16 v[62:65], v[134:137], v[230:233], v[62:65]
	ds_read_b128 v[190:193], v176 offset:4096
	v_mfma_f32_16x16x32_bf16 v[58:61], v[142:145], v[230:233], v[58:61]
	v_mfma_f32_16x16x32_bf16 v[54:57], v[134:137], v[238:241], v[54:57]
	ds_read_b128 v[194:197], v176 offset:5120
	v_mfma_f32_16x16x32_bf16 v[46:49], v[142:145], v[238:241], v[46:49]
	v_mfma_f32_16x16x32_bf16 v[38:41], v[134:137], v[246:249], v[38:41]
	ds_read_b128 v[198:201], v176 offset:6144
	v_mfma_f32_16x16x32_bf16 v[30:33], v[142:145], v[246:249], v[30:33]
	v_mfma_f32_16x16x32_bf16 v[22:25], v[134:137], v[222:225], v[22:25]
	ds_read_b128 v[202:205], v176 offset:7168
	v_mfma_f32_16x16x32_bf16 v[14:17], v[142:145], v[222:225], v[14:17]
	s_barrier
	s_add_u32 s30, s30, 0x160080
	s_addc_u32 s31, s31, 0
	s_add_i32 s84, s84, s40
	s_mov_b32 m0, s84
	s_nop 0
	global_load_lds_dwordx4 v146, s[30:31]
	s_add_i32 m0, s84, 0x2000
	s_nop 0
	global_load_lds_dwordx4 v148, s[30:31]
	s_waitcnt vmcnt(10)
	s_barrier
	s_waitcnt lgkmcnt(0)
	v_mfma_f32_16x16x32_bf16 v[50:53], v[206:209], v[226:229], v[50:53]
	ds_read_b128 v[126:129], v175
	v_mfma_f32_16x16x32_bf16 v[42:45], v[214:217], v[226:229], v[42:45]
	v_mfma_f32_16x16x32_bf16 v[34:37], v[206:209], v[234:237], v[34:37]
	v_mfma_f32_16x16x32_bf16 v[26:29], v[214:217], v[234:237], v[26:29]
	v_mfma_f32_16x16x32_bf16 v[18:21], v[206:209], v[242:245], v[18:21]
	ds_read_b128 v[134:137], v175 offset:1024
	v_mfma_f32_16x16x32_bf16 v[10:13], v[214:217], v[242:245], v[10:13]
	v_mfma_f32_16x16x32_bf16 v[6:9], v[206:209], v[250:253], v[6:9]
	v_mfma_f32_16x16x32_bf16 v[2:5], v[214:217], v[250:253], v[2:5]
	v_mfma_f32_16x16x32_bf16 v[50:53], v[210:213], v[230:233], v[50:53]
	ds_read_b128 v[138:141], v175 offset:2048
	v_mfma_f32_16x16x32_bf16 v[42:45], v[218:221], v[230:233], v[42:45]
	v_mfma_f32_16x16x32_bf16 v[34:37], v[210:213], v[238:241], v[34:37]
	v_mfma_f32_16x16x32_bf16 v[26:29], v[218:221], v[238:241], v[26:29]
	v_mfma_f32_16x16x32_bf16 v[18:21], v[210:213], v[246:249], v[18:21]
	ds_read_b128 v[142:145], v175 offset:3072
	v_mfma_f32_16x16x32_bf16 v[10:13], v[218:221], v[246:249], v[10:13]
	v_mfma_f32_16x16x32_bf16 v[6:9], v[210:213], v[222:225], v[6:9]
	v_mfma_f32_16x16x32_bf16 v[2:5], v[218:221], v[222:225], v[2:5]
	s_add_i32 s60, s60, 2
	s_add_u32 s28, s28, 0x100
	s_addc_u32 s29, s29, 0
	s_add_u32 s58, s58, 0x100
	s_addc_u32 s59, s59, 0
	s_cmpk_gt_u32 s60, 0x55
	s_cbranch_scc0 .LBB0_1297
	s_barrier
